# features stage A (token-shift lerp): previous-row and next-row loads issued together with the centre-row load, one wait instead of three (9 unrolled iterations + LoRA-input stage)
# baseline (speedup 1.0000x reference)
; #define UFOR(v, n) _Pragma("unroll") for (int v = 0; v < (n); ++v)
; __device__ __forceinline__ void phase_features(KP p, int l) {
;     ...
;     for (int i = 0; i < 9; ++i) {
;       const int q = tid_ + 512 * i, tok = q / 288, grp = q % 288, sec = grp / 96, r = R0 + tok, col = grp * 8, ch = col - sec * RW;
;       const bool hm = r - 1 >= s0, hp = r + 1 < s0 + len;
;       const u16* z = zrw + (size_t)r * RWC + col;
;       float c[8], a[8], b[8], o[8], m[8];
;       unpack8(*(const uint4*)z, c);
;       if (hm) unpack8(*(const uint4*)(z - RWC), a); else UFOR(x, 8) a[x] = 0.f;
;       if (hp) unpack8(*(const uint4*)(z + RWC), b); else UFOR(x, 8) b[x] = 0.f;
;       ld8f(mu + col, m);
;       UFOR(x, 8) o[x] = c[x] + (0.5f * (a[x] + b[x]) - c[x]) * m[x];
;       const uint4 pk = pack8(o);
;       const size_t go = (size_t)r * RW + ch;
;       if (sec == 0) { *(uint4*)(FA(0) + go) = pk; *(uint4*)(smem + F_RL + (tok * RW + ch) * 2) = pk; }
.Lfeat_pf_done:
	s_lshl_b32 s15, s14, 4
	v_add_u32_e32 v24, s15, v166
	s_movk_i32 s1, 0x1400
	v_mad_i64_i32 v[4:5], s[6:7], v24, s1, v[46:47]
	global_load_dwordx4 v[0:3], v[4:5], off
	s_cmpk_lt_i32 s14, 0x800
	s_cselect_b64 s[52:53], -1, 0
	s_and_b64 s[6:7], s[52:53], exec
	s_mov_b32 s1, 0x7fffff00
	s_cselect_b32 s6, 0xffffc000, s1
	s_and_b32 s38, s6, s15
	v_cmp_lt_i32_e32 vcc, s38, v24
	v_mov_b32_e32 v16, 0
	v_mov_b32_e32 v17, 0
	v_mov_b32_e32 v18, 0
	v_mov_b32_e32 v19, 0
	v_mov_b32_e32 v212, 0
	v_mov_b32_e32 v213, 0
	v_mov_b32_e32 v214, 0
	v_mov_b32_e32 v215, 0
	s_and_saveexec_b64 s[56:57], vcc
	s_cbranch_execz .LBB0_527
	v_add_co_u32_e32 v6, vcc, 0xfffff000, v4
	s_nop 1
	v_addc_co_u32_e32 v7, vcc, -1, v5, vcc
	global_load_dwordx4 v[16:19], v[6:7], off offset:-1024
.LBB0_527:
	s_or_b64 exec, exec, s[56:57]
	s_and_b64 s[6:7], s[52:53], exec
	s_movk_i32 s6, 0x4000
	s_cselect_b32 s6, s6, 0x100
	s_add_i32 s39, s38, s6
	v_add_u32_e32 v9, 1, v24
	v_cmp_gt_i32_e32 vcc, s39, v9
	s_and_saveexec_b64 s[52:53], vcc
	s_cbranch_execz .LBB0_529
	v_add_co_u32_e32 v4, vcc, 0x1000, v4
	s_nop 1
	v_addc_co_u32_e32 v5, vcc, 0, v5, vcc
	global_load_dwordx4 v[212:215], v[4:5], off offset:1024
.LBB0_529:
	s_or_b64 exec, exec, s[52:53]
	s_waitcnt vmcnt(0)
	v_lshlrev_b32_e32 v12, 16, v16
	v_and_b32_e32 v13, 0xffff0000, v16
	v_lshlrev_b32_e32 v6, 16, v17
	v_and_b32_e32 v7, 0xffff0000, v17
	v_lshlrev_b32_e32 v16, 16, v18
	v_and_b32_e32 v17, 0xffff0000, v18
	v_lshlrev_b32_e32 v14, 16, v19
	v_and_b32_e32 v15, 0xffff0000, v19
	v_lshlrev_b32_e32 v8, 16, v212
	v_and_b32_e32 v9, 0xffff0000, v212
	v_lshlrev_b32_e32 v18, 16, v213
	v_and_b32_e32 v19, 0xffff0000, v213
	v_lshlrev_b32_e32 v22, 16, v214
	v_and_b32_e32 v23, 0xffff0000, v214
	v_lshlrev_b32_e32 v20, 16, v215
	v_and_b32_e32 v21, 0xffff0000, v215
	v_lshlrev_b32_e32 v33, 16, v3
	v_lshlrev_b32_e32 v32, 16, v2
	v_and_b32_e32 v11, 0xffff0000, v3
	v_and_b32_e32 v10, 0xffff0000, v2
	global_load_dwordx4 v[2:5], v[48:49], off offset:16
	global_load_dwordx4 v[26:29], v[48:49], off
	v_pk_add_f32 v[8:9], v[12:13], v[8:9]
	v_pk_add_f32 v[12:13], v[6:7], v[18:19]
	v_lshlrev_b32_e32 v31, 16, v1
	v_lshlrev_b32_e32 v30, 16, v0
	v_mov_b32_e32 v6, v8
	v_mov_b32_e32 v7, v12
	v_and_b32_e32 v1, 0xffff0000, v1
	v_and_b32_e32 v0, 0xffff0000, v0
	v_pk_fma_f32 v[6:7], v[6:7], 0.5, v[30:31] op_sel_hi:[1,0,1] neg_lo:[0,0,1] neg_hi:[0,0,1]
	v_mov_b32_e32 v12, v9
	v_pk_fma_f32 v[8:9], v[12:13], 0.5, v[0:1] op_sel_hi:[1,0,1] neg_lo:[0,0,1] neg_hi:[0,0,1]
	v_pk_add_f32 v[16:17], v[16:17], v[22:23]
	v_pk_add_f32 v[14:15], v[14:15], v[20:21]
	s_waitcnt vmcnt(0)
	v_mov_b32_e32 v18, v26
	v_mov_b32_e32 v19, v28
	v_pk_fma_f32 v[6:7], v[18:19], v[6:7], v[30:31]
	v_mov_b32_e32 v28, v27
	v_pk_fma_f32 v[8:9], v[28:29], v[8:9], v[0:1]
	v_and_b32_sdwa v1, v6, v207 dst_sel:DWORD dst_unused:UNUSED_PAD src0_sel:WORD_1 src1_sel:DWORD
	v_add3_u32 v12, v6, v1, s31
	v_and_b32_sdwa v1, v9, v207 dst_sel:DWORD dst_unused:UNUSED_PAD src0_sel:WORD_1 src1_sel:DWORD
	v_and_b32_sdwa v13, v8, v207 dst_sel:DWORD dst_unused:UNUSED_PAD src0_sel:WORD_1 src1_sel:DWORD
	v_and_b32_sdwa v0, v7, v207 dst_sel:DWORD dst_unused:UNUSED_PAD src0_sel:WORD_1 src1_sel:DWORD
	v_add3_u32 v1, v9, v1, s31
	v_add3_u32 v13, v8, v13, s31
	v_add3_u32 v0, v7, v0, s31
	v_and_b32_e32 v1, 0xffff0000, v1
	v_and_b32_e32 v13, 0xffff0000, v13
	v_or_b32_sdwa v1, v1, v0 dst_sel:DWORD dst_unused:UNUSED_PAD src0_sel:DWORD src1_sel:WORD_1
	v_or_b32_sdwa v0, v13, v12 dst_sel:DWORD dst_unused:UNUSED_PAD src0_sel:DWORD src1_sel:WORD_1
	v_mov_b32_e32 v12, v16
	v_mov_b32_e32 v13, v14
	v_pk_fma_f32 v[12:13], v[12:13], 0.5, v[32:33] op_sel_hi:[1,0,1] neg_lo:[0,0,1] neg_hi:[0,0,1]
	v_mov_b32_e32 v18, v2
	v_mov_b32_e32 v19, v4
	v_mov_b32_e32 v14, v17
	v_pk_fma_f32 v[12:13], v[12:13], v[18:19], v[32:33]
	v_pk_fma_f32 v[14:15], v[14:15], 0.5, v[10:11] op_sel_hi:[1,0,1] neg_lo:[0,0,1] neg_hi:[0,0,1]
	v_mov_b32_e32 v4, v3
	v_pk_fma_f32 v[4:5], v[14:15], v[4:5], v[10:11]
	v_and_b32_sdwa v3, v12, v207 dst_sel:DWORD dst_unused:UNUSED_PAD src0_sel:WORD_1 src1_sel:DWORD
	v_add3_u32 v10, v12, v3, s31
	v_and_b32_sdwa v3, v5, v207 dst_sel:DWORD dst_unused:UNUSED_PAD src0_sel:WORD_1 src1_sel:DWORD
	v_and_b32_sdwa v11, v4, v207 dst_sel:DWORD dst_unused:UNUSED_PAD src0_sel:WORD_1 src1_sel:DWORD
	v_and_b32_sdwa v2, v13, v207 dst_sel:DWORD dst_unused:UNUSED_PAD src0_sel:WORD_1 src1_sel:DWORD
	v_add3_u32 v3, v5, v3, s31
	v_add3_u32 v11, v4, v11, s31
	v_add3_u32 v2, v13, v2, s31
	v_and_b32_e32 v3, 0xffff0000, v3
	v_and_b32_e32 v11, 0xffff0000, v11
	v_or_b32_sdwa v3, v3, v2 dst_sel:DWORD dst_unused:UNUSED_PAD src0_sel:DWORD src1_sel:WORD_1
	v_or_b32_sdwa v2, v11, v10 dst_sel:DWORD dst_unused:UNUSED_PAD src0_sel:DWORD src1_sel:WORD_1
	v_mad_i64_i32 v[10:11], s[6:7], v24, s0, v[52:53]
	s_mov_b64 s[6:7], exec
	v_readlane_b32 s18, v255, 19
	v_readlane_b32 s19, v255, 20
	s_and_b64 s[18:19], s[6:7], s[18:19]
	s_xor_b64 s[52:53], s[18:19], s[6:7]
	s_mov_b64 exec, s[18:19]
	s_cbranch_execz .LBB0_535
; #define UFOR(v, n) _Pragma("unroll") for (int v = 0; v < (n); ++v)
; __device__ __forceinline__ void phase_features(KP p, int l) {
;     ...
;       else {
;         *(uint4*)(smem + F_KL + (tok * RW + ch) * 2) = pk;
;         float kc[8], kq[8]; ld8f(kk_ + ch, kc);
;         float ss = 0.f;
;         UFOR(x, 8) { kq[x] = o[x] * kc[x]; ss += kq[x] * kq[x]; }
;         ss += dppf<0xB1>(ss); ss += dppf<0x4E>(ss); ss += dppf<0x141>(ss);
;         const float inv = 1.f / fmaxf(sqrtf(ss), 1e-12f);
;         UFOR(x, 8) kq[x] *= inv;
;         const uint4 pq = pack8(kq);
;         *(uint4*)(FA(1) + go) = pq; *(uint4*)(smem + F_KK + (tok * RW + ch) * 2) = pq;
	s_mov_b64 s[6:7], exec
	v_readlane_b32 s18, v255, 31
	v_readlane_b32 s19, v255, 32
	s_and_b64 s[18:19], s[6:7], s[18:19]
	s_xor_b64 s[56:57], s[18:19], s[6:7]
	s_mov_b64 exec, s[18:19]
	s_cbranch_execz .LBB0_532
	v_add_u32_e32 v22, 0, v168
	ds_write_b128 v22, v[0:3] offset:8448
	global_load_dwordx4 v[14:17], v[54:55], off offset:16
	global_load_dwordx4 v[18:21], v[54:55], off
	v_lshl_add_u64 v[0:1], v[10:11], 1, s[76:77]
	s_mov_b32 s1, 0xf800000
	s_waitcnt vmcnt(1)
	v_mov_b32_e32 v11, v16
	s_waitcnt vmcnt(0)
	v_mov_b32_e32 v2, v18
	v_mov_b32_e32 v3, v20
	v_mov_b32_e32 v20, v19
	v_pk_mul_f32 v[2:3], v[6:7], v[2:3]
	v_pk_mul_f32 v[6:7], v[8:9], v[20:21]
	v_mov_b32_e32 v16, v15
	v_mov_b32_e32 v8, v3
	v_mov_b32_e32 v9, v7
	v_mov_b32_e32 v10, v14
	v_pk_mul_f32 v[4:5], v[4:5], v[16:17]
	v_mul_f32_e32 v16, v2, v2
	v_pk_mul_f32 v[8:9], v[8:9], v[8:9]
	v_pk_mul_f32 v[10:11], v[12:13], v[10:11]
	v_fmac_f32_e32 v16, v6, v6
	v_mov_b32_e32 v12, v10
	v_mov_b32_e32 v13, v4
	v_add_f32_e32 v8, v16, v8
	v_pk_mul_f32 v[12:13], v[12:13], v[12:13]
	v_add_f32_e32 v8, v8, v9
	v_mov_b32_e32 v14, v11
	v_mov_b32_e32 v15, v5
	v_add_f32_e32 v8, v8, v12
	v_pk_mul_f32 v[14:15], v[14:15], v[14:15]
	v_add_f32_e32 v8, v8, v13
	v_add_f32_e32 v8, v8, v14
	v_add_f32_e32 v8, v8, v15
	s_nop 1
	v_add_f32_dpp v8, v8, v8 quad_perm:[1,0,3,2] row_mask:0xf bank_mask:0xf bound_ctrl:1
	s_nop 1
	v_add_f32_dpp v8, v8, v8 quad_perm:[2,3,0,1] row_mask:0xf bank_mask:0xf bound_ctrl:1
	s_nop 1
	v_add_f32_dpp v8, v8, v8 row_half_mirror row_mask:0xf bank_mask:0xf bound_ctrl:1
	v_cmp_gt_f32_e32 vcc, s1, v8
	v_mul_f32_e32 v9, 0x4f800000, v8
	s_nop 0
	v_cndmask_b32_e32 v8, v8, v9, vcc
	v_sqrt_f32_e32 v9, v8
	s_nop 0
	v_add_u32_e32 v12, -1, v9
	v_fma_f32 v13, -v12, v9, v8
	v_cmp_ge_f32_e64 s[84:85], 0, v13
	v_add_u32_e32 v13, 1, v9
	s_nop 0
	v_cndmask_b32_e64 v12, v9, v12, s[84:85]
	v_fma_f32 v9, -v13, v9, v8
	v_cmp_lt_f32_e64 s[84:85], 0, v9
	s_nop 1
	v_cndmask_b32_e64 v9, v12, v13, s[84:85]
	v_mul_f32_e32 v12, 0x37800000, v9
	v_cndmask_b32_e32 v9, v9, v12, vcc
	v_mov_b32_e32 v12, 0x260
	v_cmp_class_f32_e32 vcc, v8, v12
	s_nop 1
	v_cndmask_b32_e32 v8, v9, v8, vcc
	v_max_f32_e32 v8, 0x2b8cbccc, v8
	v_div_scale_f32 v9, s[6:7], v8, v8, 1.0
	v_rcp_f32_e32 v12, v9
	s_nop 0
	v_fma_f32 v13, -v9, v12, 1.0
	v_fmac_f32_e32 v12, v13, v12
	v_div_scale_f32 v13, vcc, 1.0, v8, 1.0
	v_mul_f32_e32 v14, v13, v12
	v_fma_f32 v15, -v9, v14, v13
	v_fmac_f32_e32 v14, v15, v12
	v_fma_f32 v9, -v9, v14, v13
	v_div_fmas_f32 v9, v9, v12, v14
	v_div_fixup_f32 v8, v9, v8, 1.0
	v_pk_mul_f32 v[2:3], v[2:3], v[8:9] op_sel_hi:[1,0]
	v_pk_mul_f32 v[6:7], v[6:7], v[8:9] op_sel_hi:[1,0]
	v_pk_mul_f32 v[10:11], v[10:11], v[8:9] op_sel_hi:[1,0]
	v_pk_mul_f32 v[4:5], v[4:5], v[8:9] op_sel_hi:[1,0]
	v_and_b32_sdwa v8, v3, v207 dst_sel:DWORD dst_unused:UNUSED_PAD src0_sel:WORD_1 src1_sel:DWORD
	v_and_b32_sdwa v9, v2, v207 dst_sel:DWORD dst_unused:UNUSED_PAD src0_sel:WORD_1 src1_sel:DWORD
	v_add3_u32 v2, v2, v9, s31
	v_add3_u32 v3, v3, v8, s31
	v_and_b32_sdwa v8, v7, v207 dst_sel:DWORD dst_unused:UNUSED_PAD src0_sel:WORD_1 src1_sel:DWORD
	v_and_b32_sdwa v9, v6, v207 dst_sel:DWORD dst_unused:UNUSED_PAD src0_sel:WORD_1 src1_sel:DWORD
	v_add3_u32 v7, v7, v8, s31
	v_add3_u32 v6, v6, v9, s31
	v_and_b32_e32 v7, 0xffff0000, v7
	v_and_b32_e32 v6, 0xffff0000, v6
	v_and_b32_sdwa v8, v5, v207 dst_sel:DWORD dst_unused:UNUSED_PAD src0_sel:WORD_1 src1_sel:DWORD
	v_and_b32_sdwa v9, v4, v207 dst_sel:DWORD dst_unused:UNUSED_PAD src0_sel:WORD_1 src1_sel:DWORD
	v_or_b32_sdwa v3, v7, v3 dst_sel:DWORD dst_unused:UNUSED_PAD src0_sel:DWORD src1_sel:WORD_1
	v_or_b32_sdwa v2, v6, v2 dst_sel:DWORD dst_unused:UNUSED_PAD src0_sel:DWORD src1_sel:WORD_1
	v_and_b32_sdwa v6, v11, v207 dst_sel:DWORD dst_unused:UNUSED_PAD src0_sel:WORD_1 src1_sel:DWORD
	v_and_b32_sdwa v7, v10, v207 dst_sel:DWORD dst_unused:UNUSED_PAD src0_sel:WORD_1 src1_sel:DWORD
	v_add3_u32 v5, v5, v8, s31
	v_add3_u32 v4, v4, v9, s31
	v_add3_u32 v7, v10, v7, s31
	v_add3_u32 v6, v11, v6, s31
	v_and_b32_e32 v5, 0xffff0000, v5
	v_and_b32_e32 v4, 0xffff0000, v4
	v_or_b32_sdwa v5, v5, v6 dst_sel:DWORD dst_unused:UNUSED_PAD src0_sel:DWORD src1_sel:WORD_1
	v_or_b32_sdwa v4, v4, v7 dst_sel:DWORD dst_unused:UNUSED_PAD src0_sel:DWORD src1_sel:WORD_1
	global_store_dwordx4 v[0:1], v[2:5], off
	ds_write_b128 v22, v[2:5] offset:33024

; #define UFOR(v, n) _Pragma("unroll") for (int v = 0; v < (n); ++v)
; __device__ __forceinline__ void phase_features(KP p, int l) {
;     ...
;       const int q = tid_ + 512 * i, tok = q / 288, grp = q % 288, sec = grp / 96, r = R0 + tok, col = grp * 8, ch = col - sec * RW;
;       const bool hm = r - 1 >= s0, hp = r + 1 < s0 + len;
;       const u16* z = zrw + (size_t)r * RWC + col;
;       float c[8], a[8], b[8], o[8], m[8];
;       unpack8(*(const uint4*)z, c);
;       if (hm) unpack8(*(const uint4*)(z - RWC), a); else UFOR(x, 8) a[x] = 0.f;
;       if (hp) unpack8(*(const uint4*)(z + RWC), b); else UFOR(x, 8) b[x] = 0.f;
;       ld8f(mu + col, m);
;       UFOR(x, 8) o[x] = c[x] + (0.5f * (a[x] + b[x]) - c[x]) * m[x];
;       const uint4 pk = pack8(o);
;       const size_t go = (size_t)r * RW + ch;
;       if (sec == 0) { *(uint4*)(FA(0) + go) = pk; *(uint4*)(smem + F_RL + (tok * RW + ch) * 2) = pk; }
.LBB0_537:
	s_or_b64 exec, exec, s[52:53]
	v_add_u32_e32 v22, s15, v167
	s_movk_i32 s1, 0x1400
	v_mad_i64_i32 v[6:7], s[6:7], v22, s1, v[56:57]
	global_load_dwordx4 v[0:3], v[6:7], off
	v_cmp_lt_i32_e32 vcc, s38, v22
	v_mov_b32_e32 v14, 0
	v_mov_b32_e32 v15, 0
	v_mov_b32_e32 v16, 0
	v_mov_b32_e32 v17, 0
	v_mov_b32_e32 v212, 0
	v_mov_b32_e32 v213, 0
	v_mov_b32_e32 v214, 0
	v_mov_b32_e32 v215, 0
	s_and_saveexec_b64 s[52:53], vcc
	s_cbranch_execz .LBB0_539
	v_add_co_u32_e32 v4, vcc, 0xfffff000, v6
	s_nop 1
	v_addc_co_u32_e32 v5, vcc, -1, v7, vcc
	global_load_dwordx4 v[14:17], v[4:5], off offset:-1024
.LBB0_539:
	s_or_b64 exec, exec, s[52:53]
	v_add_u32_e32 v9, 1, v22
	v_cmp_gt_i32_e32 vcc, s39, v9
	s_and_saveexec_b64 s[52:53], vcc
	s_cbranch_execz .LBB0_541
	v_add_co_u32_e32 v6, vcc, 0x1000, v6
	s_nop 1
	v_addc_co_u32_e32 v7, vcc, 0, v7, vcc
	global_load_dwordx4 v[212:215], v[6:7], off offset:1024
.LBB0_541:
	s_or_b64 exec, exec, s[52:53]
	s_waitcnt vmcnt(0)
	v_lshlrev_b32_e32 v10, 16, v14
	v_and_b32_e32 v11, 0xffff0000, v14
	v_lshlrev_b32_e32 v4, 16, v15
	v_and_b32_e32 v5, 0xffff0000, v15
	v_lshlrev_b32_e32 v14, 16, v16
	v_and_b32_e32 v15, 0xffff0000, v16
	v_lshlrev_b32_e32 v12, 16, v17
	v_and_b32_e32 v13, 0xffff0000, v17
	v_lshlrev_b32_e32 v8, 16, v212
	v_and_b32_e32 v9, 0xffff0000, v212
	v_lshlrev_b32_e32 v16, 16, v213
	v_and_b32_e32 v17, 0xffff0000, v213
	v_lshlrev_b32_e32 v20, 16, v214
	v_and_b32_e32 v21, 0xffff0000, v214
	v_lshlrev_b32_e32 v18, 16, v215
	v_and_b32_e32 v19, 0xffff0000, v215
	v_lshlrev_b32_e32 v29, 16, v1
	v_lshlrev_b32_e32 v28, 16, v0
	v_and_b32_e32 v31, 0xffff0000, v1
	v_and_b32_e32 v30, 0xffff0000, v0
	v_lshlrev_b32_e32 v33, 16, v3
	v_lshlrev_b32_e32 v32, 16, v2
	v_and_b32_e32 v7, 0xffff0000, v3
	v_and_b32_e32 v6, 0xffff0000, v2
	global_load_dwordx4 v[0:3], v[58:59], off offset:16
	global_load_dwordx4 v[24:27], v[58:59], off
	v_pk_add_f32 v[10:11], v[10:11], v[8:9]
	v_pk_add_f32 v[4:5], v[4:5], v[16:17]
	v_mov_b32_e32 v8, v10
	v_mov_b32_e32 v9, v4
	v_pk_add_f32 v[18:19], v[12:13], v[18:19]
	v_pk_fma_f32 v[8:9], v[8:9], 0.5, v[28:29] op_sel_hi:[1,0,1] neg_lo:[0,0,1] neg_hi:[0,0,1]
	v_mov_b32_e32 v4, v11
	v_pk_fma_f32 v[4:5], v[4:5], 0.5, v[30:31] op_sel_hi:[1,0,1] neg_lo:[0,0,1] neg_hi:[0,0,1]
	v_pk_add_f32 v[14:15], v[14:15], v[20:21]
	s_waitcnt vmcnt(1)
	v_mov_b32_e32 v17, v2
	s_waitcnt vmcnt(0)
	v_mov_b32_e32 v12, v24
	v_mov_b32_e32 v13, v26
	v_pk_fma_f32 v[8:9], v[12:13], v[8:9], v[28:29]
	v_mov_b32_e32 v26, v25
	v_pk_fma_f32 v[10:11], v[26:27], v[4:5], v[30:31]
	v_and_b32_sdwa v5, v8, v207 dst_sel:DWORD dst_unused:UNUSED_PAD src0_sel:WORD_1 src1_sel:DWORD
	v_add3_u32 v12, v8, v5, s31
	v_and_b32_sdwa v5, v11, v207 dst_sel:DWORD dst_unused:UNUSED_PAD src0_sel:WORD_1 src1_sel:DWORD
	v_and_b32_sdwa v13, v10, v207 dst_sel:DWORD dst_unused:UNUSED_PAD src0_sel:WORD_1 src1_sel:DWORD
	v_and_b32_sdwa v4, v9, v207 dst_sel:DWORD dst_unused:UNUSED_PAD src0_sel:WORD_1 src1_sel:DWORD
	v_add3_u32 v5, v11, v5, s31
	v_add3_u32 v13, v10, v13, s31
	v_add3_u32 v4, v9, v4, s31
	v_and_b32_e32 v5, 0xffff0000, v5
	v_and_b32_e32 v13, 0xffff0000, v13
	v_or_b32_sdwa v5, v5, v4 dst_sel:DWORD dst_unused:UNUSED_PAD src0_sel:DWORD src1_sel:WORD_1
	v_or_b32_sdwa v4, v13, v12 dst_sel:DWORD dst_unused:UNUSED_PAD src0_sel:DWORD src1_sel:WORD_1
	v_mov_b32_e32 v13, v18
	v_mov_b32_e32 v18, v15
	v_mov_b32_e32 v12, v14
	v_pk_fma_f32 v[14:15], v[18:19], 0.5, v[6:7] op_sel_hi:[1,0,1] neg_lo:[0,0,1] neg_hi:[0,0,1]
	v_mov_b32_e32 v2, v1
	v_pk_fma_f32 v[12:13], v[12:13], 0.5, v[32:33] op_sel_hi:[1,0,1] neg_lo:[0,0,1] neg_hi:[0,0,1]
	v_mov_b32_e32 v16, v0
	v_pk_fma_f32 v[2:3], v[14:15], v[2:3], v[6:7]
	v_pk_fma_f32 v[12:13], v[12:13], v[16:17], v[32:33]
	v_and_b32_sdwa v6, v3, v207 dst_sel:DWORD dst_unused:UNUSED_PAD src0_sel:WORD_1 src1_sel:DWORD
	v_and_b32_sdwa v7, v2, v207 dst_sel:DWORD dst_unused:UNUSED_PAD src0_sel:WORD_1 src1_sel:DWORD
	v_and_b32_sdwa v0, v13, v207 dst_sel:DWORD dst_unused:UNUSED_PAD src0_sel:WORD_1 src1_sel:DWORD
	v_and_b32_sdwa v1, v12, v207 dst_sel:DWORD dst_unused:UNUSED_PAD src0_sel:WORD_1 src1_sel:DWORD
	v_add3_u32 v6, v3, v6, s31
	v_add3_u32 v7, v2, v7, s31
	v_add3_u32 v1, v12, v1, s31
	v_add3_u32 v0, v13, v0, s31
	v_and_b32_e32 v6, 0xffff0000, v6
	v_and_b32_e32 v14, 0xffff0000, v7
	v_or_b32_sdwa v7, v6, v0 dst_sel:DWORD dst_unused:UNUSED_PAD src0_sel:DWORD src1_sel:WORD_1
	v_or_b32_sdwa v6, v14, v1 dst_sel:DWORD dst_unused:UNUSED_PAD src0_sel:DWORD src1_sel:WORD_1
	v_mad_i64_i32 v[0:1], s[6:7], v22, s0, v[50:51]
	s_mov_b64 s[6:7], exec
	v_readlane_b32 s18, v255, 23
	v_readlane_b32 s19, v255, 24
	s_and_b64 s[18:19], s[6:7], s[18:19]
	s_xor_b64 s[52:53], s[18:19], s[6:7]
	s_mov_b64 exec, s[18:19]
	s_cbranch_execz .LBB0_547
; #define UFOR(v, n) _Pragma("unroll") for (int v = 0; v < (n); ++v)
; __device__ __forceinline__ void phase_features(KP p, int l) {
;     ...
;       else {
;         *(uint4*)(smem + F_KL + (tok * RW + ch) * 2) = pk;
;         float kc[8], kq[8]; ld8f(kk_ + ch, kc);
;         float ss = 0.f;
;         UFOR(x, 8) { kq[x] = o[x] * kc[x]; ss += kq[x] * kq[x]; }
;         ss += dppf<0xB1>(ss); ss += dppf<0x4E>(ss); ss += dppf<0x141>(ss);
;         const float inv = 1.f / fmaxf(sqrtf(ss), 1e-12f);
;         UFOR(x, 8) kq[x] *= inv;
;         const uint4 pq = pack8(kq);
;         *(uint4*)(FA(1) + go) = pq; *(uint4*)(smem + F_KK + (tok * RW + ch) * 2) = pq;
	s_mov_b64 s[6:7], exec
	v_readlane_b32 s18, v255, 33
	v_readlane_b32 s19, v255, 34
	s_and_b64 s[18:19], s[6:7], s[18:19]
	s_xor_b64 s[56:57], s[18:19], s[6:7]
	s_mov_b64 exec, s[18:19]
	s_cbranch_execz .LBB0_544
	v_add_u32_e32 v20, 0, v169
	ds_write_b128 v20, v[4:7] offset:8448
	global_load_dwordx4 v[4:7], v[60:61], off offset:16
	global_load_dwordx4 v[14:17], v[60:61], off
	s_mov_b32 s1, 0xf800000
	v_lshl_add_u64 v[0:1], v[0:1], 1, s[76:77]
	s_waitcnt vmcnt(0)
	v_mov_b32_e32 v18, v14
	v_mov_b32_e32 v19, v16
	v_mov_b32_e32 v16, v15
	v_pk_mul_f32 v[8:9], v[8:9], v[18:19]
	v_pk_mul_f32 v[10:11], v[10:11], v[16:17]
	v_mov_b32_e32 v16, v4
	v_mov_b32_e32 v17, v6
	v_mov_b32_e32 v14, v9
	v_mov_b32_e32 v15, v11
	v_pk_mul_f32 v[12:13], v[12:13], v[16:17]
	v_mov_b32_e32 v6, v5
	v_mul_f32_e32 v16, v8, v8
	v_pk_mul_f32 v[14:15], v[14:15], v[14:15]
	v_pk_mul_f32 v[2:3], v[2:3], v[6:7]
	v_fmac_f32_e32 v16, v10, v10
	v_mov_b32_e32 v4, v12
	v_mov_b32_e32 v5, v2
	v_add_f32_e32 v14, v16, v14
	v_pk_mul_f32 v[4:5], v[4:5], v[4:5]
	v_add_f32_e32 v14, v14, v15
	v_mov_b32_e32 v6, v13
	v_mov_b32_e32 v7, v3
	v_add_f32_e32 v4, v14, v4
	v_pk_mul_f32 v[6:7], v[6:7], v[6:7]
	v_add_f32_e32 v4, v4, v5
	v_add_f32_e32 v4, v4, v6
	v_add_f32_e32 v4, v4, v7
	s_nop 1
	v_add_f32_dpp v4, v4, v4 quad_perm:[1,0,3,2] row_mask:0xf bank_mask:0xf bound_ctrl:1
	s_nop 1
	v_add_f32_dpp v4, v4, v4 quad_perm:[2,3,0,1] row_mask:0xf bank_mask:0xf bound_ctrl:1
	s_nop 1
	v_add_f32_dpp v4, v4, v4 row_half_mirror row_mask:0xf bank_mask:0xf bound_ctrl:1
	v_cmp_gt_f32_e32 vcc, s1, v4
	v_mul_f32_e32 v5, 0x4f800000, v4
	s_nop 0
	v_cndmask_b32_e32 v4, v4, v5, vcc
	v_sqrt_f32_e32 v5, v4
	s_nop 0
	v_add_u32_e32 v6, -1, v5
	v_fma_f32 v7, -v6, v5, v4
	v_cmp_ge_f32_e64 s[84:85], 0, v7
	v_add_u32_e32 v7, 1, v5
	s_nop 0
	v_cndmask_b32_e64 v6, v5, v6, s[84:85]
	v_fma_f32 v5, -v7, v5, v4
	v_cmp_lt_f32_e64 s[84:85], 0, v5
	s_nop 1
	v_cndmask_b32_e64 v5, v6, v7, s[84:85]
	v_mul_f32_e32 v6, 0x37800000, v5
	v_cndmask_b32_e32 v5, v5, v6, vcc
	v_mov_b32_e32 v6, 0x260
	v_cmp_class_f32_e32 vcc, v4, v6
	s_nop 1
	v_cndmask_b32_e32 v4, v5, v4, vcc
	v_max_f32_e32 v4, 0x2b8cbccc, v4
	v_div_scale_f32 v5, s[6:7], v4, v4, 1.0
	v_rcp_f32_e32 v6, v5
	s_nop 0
	v_fma_f32 v7, -v5, v6, 1.0
	v_fmac_f32_e32 v6, v7, v6
	v_div_scale_f32 v7, vcc, 1.0, v4, 1.0
	v_mul_f32_e32 v14, v7, v6
	v_fma_f32 v15, -v5, v14, v7
	v_fmac_f32_e32 v14, v15, v6
	v_fma_f32 v5, -v5, v14, v7
	v_div_fmas_f32 v5, v5, v6, v14
	v_div_fixup_f32 v4, v5, v4, 1.0
	v_pk_mul_f32 v[6:7], v[8:9], v[4:5] op_sel_hi:[1,0]
	v_pk_mul_f32 v[8:9], v[10:11], v[4:5] op_sel_hi:[1,0]
	v_pk_mul_f32 v[10:11], v[12:13], v[4:5] op_sel_hi:[1,0]
	v_pk_mul_f32 v[4:5], v[2:3], v[4:5] op_sel_hi:[1,0]
	v_and_b32_sdwa v2, v7, v207 dst_sel:DWORD dst_unused:UNUSED_PAD src0_sel:WORD_1 src1_sel:DWORD
	v_and_b32_sdwa v3, v6, v207 dst_sel:DWORD dst_unused:UNUSED_PAD src0_sel:WORD_1 src1_sel:DWORD
	v_add3_u32 v6, v6, v3, s31
	v_add3_u32 v2, v7, v2, s31
	v_and_b32_sdwa v3, v9, v207 dst_sel:DWORD dst_unused:UNUSED_PAD src0_sel:WORD_1 src1_sel:DWORD
	v_and_b32_sdwa v7, v8, v207 dst_sel:DWORD dst_unused:UNUSED_PAD src0_sel:WORD_1 src1_sel:DWORD
	v_add3_u32 v3, v9, v3, s31
	v_add3_u32 v7, v8, v7, s31
	v_and_b32_e32 v3, 0xffff0000, v3
	v_and_b32_e32 v7, 0xffff0000, v7
	v_and_b32_sdwa v8, v5, v207 dst_sel:DWORD dst_unused:UNUSED_PAD src0_sel:WORD_1 src1_sel:DWORD
	v_and_b32_sdwa v9, v4, v207 dst_sel:DWORD dst_unused:UNUSED_PAD src0_sel:WORD_1 src1_sel:DWORD
	v_or_b32_sdwa v3, v3, v2 dst_sel:DWORD dst_unused:UNUSED_PAD src0_sel:DWORD src1_sel:WORD_1
	v_or_b32_sdwa v2, v7, v6 dst_sel:DWORD dst_unused:UNUSED_PAD src0_sel:DWORD src1_sel:WORD_1
	v_and_b32_sdwa v6, v11, v207 dst_sel:DWORD dst_unused:UNUSED_PAD src0_sel:WORD_1 src1_sel:DWORD
	v_and_b32_sdwa v7, v10, v207 dst_sel:DWORD dst_unused:UNUSED_PAD src0_sel:WORD_1 src1_sel:DWORD
	v_add3_u32 v5, v5, v8, s31
	v_add3_u32 v4, v4, v9, s31
	v_add3_u32 v7, v10, v7, s31
	v_add3_u32 v6, v11, v6, s31
	v_and_b32_e32 v5, 0xffff0000, v5
	v_and_b32_e32 v4, 0xffff0000, v4
	v_or_b32_sdwa v5, v5, v6 dst_sel:DWORD dst_unused:UNUSED_PAD src0_sel:DWORD src1_sel:WORD_1
	v_or_b32_sdwa v4, v4, v7 dst_sel:DWORD dst_unused:UNUSED_PAD src0_sel:DWORD src1_sel:WORD_1
	global_store_dwordx4 v[0:1], v[2:5], off
	ds_write_b128 v20, v[2:5] offset:33024

; #define UFOR(v, n) _Pragma("unroll") for (int v = 0; v < (n); ++v)
; __device__ __forceinline__ void phase_features(KP p, int l) {
;     ...
;       const int q = tid_ + 512 * i, tok = q / 288, grp = q % 288, sec = grp / 96, r = R0 + tok, col = grp * 8, ch = col - sec * RW;
;       const bool hm = r - 1 >= s0, hp = r + 1 < s0 + len;
;       const u16* z = zrw + (size_t)r * RWC + col;
;       float c[8], a[8], b[8], o[8], m[8];
;       unpack8(*(const uint4*)z, c);
;       if (hm) unpack8(*(const uint4*)(z - RWC), a); else UFOR(x, 8) a[x] = 0.f;
.LBB0_549:
	s_or_b64 exec, exec, s[52:53]
	v_add_u32_e32 v22, s15, v170
	s_movk_i32 s1, 0x1400
	v_mad_i64_i32 v[6:7], s[6:7], v22, s1, v[62:63]
	global_load_dwordx4 v[0:3], v[6:7], off
	v_cmp_lt_i32_e32 vcc, s38, v22
	v_mov_b32_e32 v14, 0
	v_mov_b32_e32 v15, 0
	v_mov_b32_e32 v16, 0
	v_mov_b32_e32 v17, 0
	v_mov_b32_e32 v212, 0
	v_mov_b32_e32 v213, 0
	v_mov_b32_e32 v214, 0
	v_mov_b32_e32 v215, 0
	s_and_saveexec_b64 s[52:53], vcc
	s_cbranch_execz .LBB0_551
	v_add_co_u32_e32 v4, vcc, 0xfffff000, v6
	s_nop 1
	v_addc_co_u32_e32 v5, vcc, -1, v7, vcc
	global_load_dwordx4 v[14:17], v[4:5], off offset:-1024

; #define UFOR(v, n) _Pragma("unroll") for (int v = 0; v < (n); ++v)
; __device__ __forceinline__ void phase_features(KP p, int l) {
;     ...
;       const bool hm = r - 1 >= s0, hp = r + 1 < s0 + len;
;       const u16* z = zrw + (size_t)r * RWC + col;
;       float c[8], a[8], b[8], o[8], m[8];
;       unpack8(*(const uint4*)z, c);
;       if (hm) unpack8(*(const uint4*)(z - RWC), a); else UFOR(x, 8) a[x] = 0.f;
;       if (hp) unpack8(*(const uint4*)(z + RWC), b); else UFOR(x, 8) b[x] = 0.f;
;       ld8f(mu + col, m);
;       UFOR(x, 8) o[x] = c[x] + (0.5f * (a[x] + b[x]) - c[x]) * m[x];
;       const uint4 pk = pack8(o);
;       const size_t go = (size_t)r * RW + ch;
;       if (sec == 0) { *(uint4*)(FA(0) + go) = pk; *(uint4*)(smem + F_RL + (tok * RW + ch) * 2) = pk; }
;       else if (sec == 2) { *(uint4*)(FA(2) + go) = pk; }
;       else {
;         *(uint4*)(smem + F_KL + (tok * RW + ch) * 2) = pk;
.LBB0_553:
	s_or_b64 exec, exec, s[52:53]
	s_waitcnt vmcnt(0)
	v_lshlrev_b32_e32 v10, 16, v14
	v_and_b32_e32 v11, 0xffff0000, v14
	v_lshlrev_b32_e32 v4, 16, v15
	v_and_b32_e32 v5, 0xffff0000, v15
	v_lshlrev_b32_e32 v14, 16, v16
	v_and_b32_e32 v15, 0xffff0000, v16
	v_lshlrev_b32_e32 v12, 16, v17
	v_and_b32_e32 v13, 0xffff0000, v17
	v_lshlrev_b32_e32 v8, 16, v212
	v_and_b32_e32 v9, 0xffff0000, v212
	v_lshlrev_b32_e32 v16, 16, v213
	v_and_b32_e32 v17, 0xffff0000, v213
	v_lshlrev_b32_e32 v20, 16, v214
	v_and_b32_e32 v21, 0xffff0000, v214
	v_lshlrev_b32_e32 v18, 16, v215
	v_and_b32_e32 v19, 0xffff0000, v215
	v_lshlrev_b32_e32 v29, 16, v1
	v_lshlrev_b32_e32 v28, 16, v0
	v_and_b32_e32 v31, 0xffff0000, v1
	v_and_b32_e32 v30, 0xffff0000, v0
	v_lshlrev_b32_e32 v33, 16, v3
	v_lshlrev_b32_e32 v32, 16, v2
	v_and_b32_e32 v7, 0xffff0000, v3
	v_and_b32_e32 v6, 0xffff0000, v2
	global_load_dwordx4 v[0:3], v[64:65], off offset:16
	global_load_dwordx4 v[24:27], v[64:65], off
	v_pk_add_f32 v[10:11], v[10:11], v[8:9]
	v_pk_add_f32 v[4:5], v[4:5], v[16:17]
	v_mov_b32_e32 v8, v10
	v_mov_b32_e32 v9, v4
	v_pk_add_f32 v[18:19], v[12:13], v[18:19]
	v_pk_fma_f32 v[8:9], v[8:9], 0.5, v[28:29] op_sel_hi:[1,0,1] neg_lo:[0,0,1] neg_hi:[0,0,1]
	v_mov_b32_e32 v4, v11
	v_pk_fma_f32 v[4:5], v[4:5], 0.5, v[30:31] op_sel_hi:[1,0,1] neg_lo:[0,0,1] neg_hi:[0,0,1]
	v_pk_add_f32 v[14:15], v[14:15], v[20:21]
	s_waitcnt vmcnt(1)
	v_mov_b32_e32 v17, v2
	s_waitcnt vmcnt(0)
	v_mov_b32_e32 v12, v24
	v_mov_b32_e32 v13, v26
	v_pk_fma_f32 v[8:9], v[12:13], v[8:9], v[28:29]
	v_mov_b32_e32 v26, v25
	v_pk_fma_f32 v[10:11], v[26:27], v[4:5], v[30:31]
	v_and_b32_sdwa v5, v8, v207 dst_sel:DWORD dst_unused:UNUSED_PAD src0_sel:WORD_1 src1_sel:DWORD
	v_add3_u32 v12, v8, v5, s31
	v_and_b32_sdwa v5, v11, v207 dst_sel:DWORD dst_unused:UNUSED_PAD src0_sel:WORD_1 src1_sel:DWORD
	v_and_b32_sdwa v13, v10, v207 dst_sel:DWORD dst_unused:UNUSED_PAD src0_sel:WORD_1 src1_sel:DWORD
	v_and_b32_sdwa v4, v9, v207 dst_sel:DWORD dst_unused:UNUSED_PAD src0_sel:WORD_1 src1_sel:DWORD
	v_add3_u32 v5, v11, v5, s31
	v_add3_u32 v13, v10, v13, s31
	v_add3_u32 v4, v9, v4, s31
	v_and_b32_e32 v5, 0xffff0000, v5
	v_and_b32_e32 v13, 0xffff0000, v13
	v_or_b32_sdwa v5, v5, v4 dst_sel:DWORD dst_unused:UNUSED_PAD src0_sel:DWORD src1_sel:WORD_1
	v_or_b32_sdwa v4, v13, v12 dst_sel:DWORD dst_unused:UNUSED_PAD src0_sel:DWORD src1_sel:WORD_1
	v_mov_b32_e32 v13, v18
	v_mov_b32_e32 v18, v15
	v_mov_b32_e32 v12, v14
	v_pk_fma_f32 v[14:15], v[18:19], 0.5, v[6:7] op_sel_hi:[1,0,1] neg_lo:[0,0,1] neg_hi:[0,0,1]
	v_mov_b32_e32 v2, v1
	v_pk_fma_f32 v[12:13], v[12:13], 0.5, v[32:33] op_sel_hi:[1,0,1] neg_lo:[0,0,1] neg_hi:[0,0,1]
	v_mov_b32_e32 v16, v0
	v_pk_fma_f32 v[2:3], v[14:15], v[2:3], v[6:7]
	v_pk_fma_f32 v[12:13], v[12:13], v[16:17], v[32:33]
	v_and_b32_sdwa v6, v3, v207 dst_sel:DWORD dst_unused:UNUSED_PAD src0_sel:WORD_1 src1_sel:DWORD
	v_and_b32_sdwa v7, v2, v207 dst_sel:DWORD dst_unused:UNUSED_PAD src0_sel:WORD_1 src1_sel:DWORD
	v_and_b32_sdwa v0, v13, v207 dst_sel:DWORD dst_unused:UNUSED_PAD src0_sel:WORD_1 src1_sel:DWORD
	v_and_b32_sdwa v1, v12, v207 dst_sel:DWORD dst_unused:UNUSED_PAD src0_sel:WORD_1 src1_sel:DWORD
	v_add3_u32 v6, v3, v6, s31
	v_add3_u32 v7, v2, v7, s31
	v_add3_u32 v1, v12, v1, s31
	v_add3_u32 v0, v13, v0, s31
	v_and_b32_e32 v6, 0xffff0000, v6
	v_and_b32_e32 v14, 0xffff0000, v7
	v_or_b32_sdwa v7, v6, v0 dst_sel:DWORD dst_unused:UNUSED_PAD src0_sel:DWORD src1_sel:WORD_1
	v_or_b32_sdwa v6, v14, v1 dst_sel:DWORD dst_unused:UNUSED_PAD src0_sel:DWORD src1_sel:WORD_1
	v_mad_i64_i32 v[0:1], s[6:7], v22, s0, v[68:69]
	s_mov_b64 s[6:7], exec
	v_readlane_b32 s18, v255, 25
	v_readlane_b32 s19, v255, 26
	s_and_b64 s[18:19], s[6:7], s[18:19]
	s_xor_b64 s[52:53], s[18:19], s[6:7]
	s_mov_b64 exec, s[18:19]
	s_cbranch_execz .LBB0_559
	s_mov_b64 s[6:7], exec
	v_readlane_b32 s18, v255, 35
	v_readlane_b32 s19, v255, 36
	s_and_b64 s[18:19], s[6:7], s[18:19]
	s_xor_b64 s[56:57], s[18:19], s[6:7]
	s_mov_b64 exec, s[18:19]
	s_cbranch_execz .LBB0_556
; #define UFOR(v, n) _Pragma("unroll") for (int v = 0; v < (n); ++v)
; __device__ __forceinline__ void phase_features(KP p, int l) {
;     ...
;       else {
;         *(uint4*)(smem + F_KL + (tok * RW + ch) * 2) = pk;
;         float kc[8], kq[8]; ld8f(kk_ + ch, kc);
;         float ss = 0.f;
;         UFOR(x, 8) { kq[x] = o[x] * kc[x]; ss += kq[x] * kq[x]; }
;         ss += dppf<0xB1>(ss); ss += dppf<0x4E>(ss); ss += dppf<0x141>(ss);
;         const float inv = 1.f / fmaxf(sqrtf(ss), 1e-12f);
;         UFOR(x, 8) kq[x] *= inv;
;         const uint4 pq = pack8(kq);
;         *(uint4*)(FA(1) + go) = pq; *(uint4*)(smem + F_KK + (tok * RW + ch) * 2) = pq;
	v_add_u32_e32 v20, 0, v172
	ds_write_b128 v20, v[4:7] offset:8448
	global_load_dwordx4 v[4:7], v[70:71], off offset:16
	global_load_dwordx4 v[14:17], v[70:71], off
	s_mov_b32 s1, 0xf800000
	v_lshl_add_u64 v[0:1], v[0:1], 1, s[76:77]
	s_waitcnt vmcnt(0)
	v_mov_b32_e32 v18, v14
	v_mov_b32_e32 v19, v16
	v_mov_b32_e32 v16, v15
	v_pk_mul_f32 v[8:9], v[8:9], v[18:19]
	v_pk_mul_f32 v[10:11], v[10:11], v[16:17]
	v_mov_b32_e32 v16, v4
	v_mov_b32_e32 v17, v6
	v_mov_b32_e32 v14, v9
	v_mov_b32_e32 v15, v11
	v_pk_mul_f32 v[12:13], v[12:13], v[16:17]
	v_mov_b32_e32 v6, v5
	v_mul_f32_e32 v16, v8, v8
	v_pk_mul_f32 v[14:15], v[14:15], v[14:15]
	v_pk_mul_f32 v[2:3], v[2:3], v[6:7]
	v_fmac_f32_e32 v16, v10, v10
	v_mov_b32_e32 v4, v12
	v_mov_b32_e32 v5, v2
	v_add_f32_e32 v14, v16, v14
	v_pk_mul_f32 v[4:5], v[4:5], v[4:5]
	v_add_f32_e32 v14, v14, v15
	v_mov_b32_e32 v6, v13
	v_mov_b32_e32 v7, v3
	v_add_f32_e32 v4, v14, v4
	v_pk_mul_f32 v[6:7], v[6:7], v[6:7]
	v_add_f32_e32 v4, v4, v5
	v_add_f32_e32 v4, v4, v6
	v_add_f32_e32 v4, v4, v7
	s_nop 1
	v_add_f32_dpp v4, v4, v4 quad_perm:[1,0,3,2] row_mask:0xf bank_mask:0xf bound_ctrl:1
	s_nop 1
	v_add_f32_dpp v4, v4, v4 quad_perm:[2,3,0,1] row_mask:0xf bank_mask:0xf bound_ctrl:1
	s_nop 1
	v_add_f32_dpp v4, v4, v4 row_half_mirror row_mask:0xf bank_mask:0xf bound_ctrl:1
	v_cmp_gt_f32_e32 vcc, s1, v4
	v_mul_f32_e32 v5, 0x4f800000, v4
	s_nop 0
	v_cndmask_b32_e32 v4, v4, v5, vcc
	v_sqrt_f32_e32 v5, v4
	s_nop 0
	v_add_u32_e32 v6, -1, v5
	v_fma_f32 v7, -v6, v5, v4
	v_cmp_ge_f32_e64 s[84:85], 0, v7
	v_add_u32_e32 v7, 1, v5
	s_nop 0
	v_cndmask_b32_e64 v6, v5, v6, s[84:85]
	v_fma_f32 v5, -v7, v5, v4
	v_cmp_lt_f32_e64 s[84:85], 0, v5
	s_nop 1
	v_cndmask_b32_e64 v5, v6, v7, s[84:85]
	v_mul_f32_e32 v6, 0x37800000, v5
	v_cndmask_b32_e32 v5, v5, v6, vcc
	v_mov_b32_e32 v6, 0x260
	v_cmp_class_f32_e32 vcc, v4, v6
	s_nop 1
	v_cndmask_b32_e32 v4, v5, v4, vcc
	v_max_f32_e32 v4, 0x2b8cbccc, v4
	v_div_scale_f32 v5, s[6:7], v4, v4, 1.0
	v_rcp_f32_e32 v6, v5
	s_nop 0
	v_fma_f32 v7, -v5, v6, 1.0
	v_fmac_f32_e32 v6, v7, v6
	v_div_scale_f32 v7, vcc, 1.0, v4, 1.0
	v_mul_f32_e32 v14, v7, v6
	v_fma_f32 v15, -v5, v14, v7
	v_fmac_f32_e32 v14, v15, v6
	v_fma_f32 v5, -v5, v14, v7
	v_div_fmas_f32 v5, v5, v6, v14
	v_div_fixup_f32 v4, v5, v4, 1.0
	v_pk_mul_f32 v[6:7], v[8:9], v[4:5] op_sel_hi:[1,0]
	v_pk_mul_f32 v[8:9], v[10:11], v[4:5] op_sel_hi:[1,0]
	v_pk_mul_f32 v[10:11], v[12:13], v[4:5] op_sel_hi:[1,0]
	v_pk_mul_f32 v[4:5], v[2:3], v[4:5] op_sel_hi:[1,0]
	v_and_b32_sdwa v2, v7, v207 dst_sel:DWORD dst_unused:UNUSED_PAD src0_sel:WORD_1 src1_sel:DWORD
	v_and_b32_sdwa v3, v6, v207 dst_sel:DWORD dst_unused:UNUSED_PAD src0_sel:WORD_1 src1_sel:DWORD
	v_add3_u32 v6, v6, v3, s31
	v_add3_u32 v2, v7, v2, s31
	v_and_b32_sdwa v3, v9, v207 dst_sel:DWORD dst_unused:UNUSED_PAD src0_sel:WORD_1 src1_sel:DWORD
	v_and_b32_sdwa v7, v8, v207 dst_sel:DWORD dst_unused:UNUSED_PAD src0_sel:WORD_1 src1_sel:DWORD
	v_add3_u32 v3, v9, v3, s31
	v_add3_u32 v7, v8, v7, s31
	v_and_b32_e32 v3, 0xffff0000, v3
	v_and_b32_e32 v7, 0xffff0000, v7
	v_and_b32_sdwa v8, v5, v207 dst_sel:DWORD dst_unused:UNUSED_PAD src0_sel:WORD_1 src1_sel:DWORD
	v_and_b32_sdwa v9, v4, v207 dst_sel:DWORD dst_unused:UNUSED_PAD src0_sel:WORD_1 src1_sel:DWORD
	v_or_b32_sdwa v3, v3, v2 dst_sel:DWORD dst_unused:UNUSED_PAD src0_sel:DWORD src1_sel:WORD_1
	v_or_b32_sdwa v2, v7, v6 dst_sel:DWORD dst_unused:UNUSED_PAD src0_sel:DWORD src1_sel:WORD_1
	v_and_b32_sdwa v6, v11, v207 dst_sel:DWORD dst_unused:UNUSED_PAD src0_sel:WORD_1 src1_sel:DWORD
	v_and_b32_sdwa v7, v10, v207 dst_sel:DWORD dst_unused:UNUSED_PAD src0_sel:WORD_1 src1_sel:DWORD
	v_add3_u32 v5, v5, v8, s31
	v_add3_u32 v4, v4, v9, s31
	v_add3_u32 v7, v10, v7, s31
	v_add3_u32 v6, v11, v6, s31
	v_and_b32_e32 v5, 0xffff0000, v5
	v_and_b32_e32 v4, 0xffff0000, v4
	v_or_b32_sdwa v5, v5, v6 dst_sel:DWORD dst_unused:UNUSED_PAD src0_sel:DWORD src1_sel:WORD_1
	v_or_b32_sdwa v4, v4, v7 dst_sel:DWORD dst_unused:UNUSED_PAD src0_sel:DWORD src1_sel:WORD_1
	global_store_dwordx4 v[0:1], v[2:5], off
	ds_write_b128 v20, v[2:5] offset:33024

; #define UFOR(v, n) _Pragma("unroll") for (int v = 0; v < (n); ++v)
; __device__ __forceinline__ void phase_features(KP p, int l) {
;     ...
;       const int q = tid_ + 512 * i, tok = q / 288, grp = q % 288, sec = grp / 96, r = R0 + tok, col = grp * 8, ch = col - sec * RW;
;       const bool hm = r - 1 >= s0, hp = r + 1 < s0 + len;
;       const u16* z = zrw + (size_t)r * RWC + col;
;       float c[8], a[8], b[8], o[8], m[8];
;       unpack8(*(const uint4*)z, c);
;       if (hm) unpack8(*(const uint4*)(z - RWC), a); else UFOR(x, 8) a[x] = 0.f;
.LBB0_561:
	s_or_b64 exec, exec, s[52:53]
	v_add_u32_e32 v22, s15, v171
	s_movk_i32 s1, 0x1400
	v_mad_i64_i32 v[6:7], s[6:7], v22, s1, v[72:73]
	global_load_dwordx4 v[0:3], v[6:7], off
	v_cmp_lt_i32_e32 vcc, s38, v22
	v_mov_b32_e32 v14, 0
	v_mov_b32_e32 v15, 0
	v_mov_b32_e32 v16, 0
	v_mov_b32_e32 v17, 0
	v_mov_b32_e32 v212, 0
	v_mov_b32_e32 v213, 0
	v_mov_b32_e32 v214, 0
	v_mov_b32_e32 v215, 0
	s_and_saveexec_b64 s[52:53], vcc
	s_cbranch_execz .LBB0_563
	v_add_co_u32_e32 v4, vcc, 0xfffff000, v6
	s_nop 1
	v_addc_co_u32_e32 v5, vcc, -1, v7, vcc
	global_load_dwordx4 v[14:17], v[4:5], off offset:-1024

; #define UFOR(v, n) _Pragma("unroll") for (int v = 0; v < (n); ++v)
; __device__ __forceinline__ void phase_features(KP p, int l) {
;     ...
;       const bool hm = r - 1 >= s0, hp = r + 1 < s0 + len;
;       const u16* z = zrw + (size_t)r * RWC + col;
;       float c[8], a[8], b[8], o[8], m[8];
;       unpack8(*(const uint4*)z, c);
;       if (hm) unpack8(*(const uint4*)(z - RWC), a); else UFOR(x, 8) a[x] = 0.f;
;       if (hp) unpack8(*(const uint4*)(z + RWC), b); else UFOR(x, 8) b[x] = 0.f;
;       ld8f(mu + col, m);
;       UFOR(x, 8) o[x] = c[x] + (0.5f * (a[x] + b[x]) - c[x]) * m[x];
;       const uint4 pk = pack8(o);
;       const size_t go = (size_t)r * RW + ch;
;       if (sec == 0) { *(uint4*)(FA(0) + go) = pk; *(uint4*)(smem + F_RL + (tok * RW + ch) * 2) = pk; }
;       else if (sec == 2) { *(uint4*)(FA(2) + go) = pk; }
;       else {
;         *(uint4*)(smem + F_KL + (tok * RW + ch) * 2) = pk;
.LBB0_565:
	s_or_b64 exec, exec, s[52:53]
	s_waitcnt vmcnt(0)
	v_lshlrev_b32_e32 v10, 16, v14
	v_and_b32_e32 v11, 0xffff0000, v14
	v_lshlrev_b32_e32 v4, 16, v15
	v_and_b32_e32 v5, 0xffff0000, v15
	v_lshlrev_b32_e32 v14, 16, v16
	v_and_b32_e32 v15, 0xffff0000, v16
	v_lshlrev_b32_e32 v12, 16, v17
	v_and_b32_e32 v13, 0xffff0000, v17
	v_lshlrev_b32_e32 v8, 16, v212
	v_and_b32_e32 v9, 0xffff0000, v212
	v_lshlrev_b32_e32 v16, 16, v213
	v_and_b32_e32 v17, 0xffff0000, v213
	v_lshlrev_b32_e32 v20, 16, v214
	v_and_b32_e32 v21, 0xffff0000, v214
	v_lshlrev_b32_e32 v18, 16, v215
	v_and_b32_e32 v19, 0xffff0000, v215
	v_lshlrev_b32_e32 v29, 16, v1
	v_lshlrev_b32_e32 v28, 16, v0
	v_and_b32_e32 v31, 0xffff0000, v1
	v_and_b32_e32 v30, 0xffff0000, v0
	v_lshlrev_b32_e32 v33, 16, v3
	v_lshlrev_b32_e32 v32, 16, v2
	v_and_b32_e32 v7, 0xffff0000, v3
	v_and_b32_e32 v6, 0xffff0000, v2
	global_load_dwordx4 v[0:3], v[74:75], off offset:16
	global_load_dwordx4 v[24:27], v[74:75], off
	v_pk_add_f32 v[10:11], v[10:11], v[8:9]
	v_pk_add_f32 v[4:5], v[4:5], v[16:17]
	v_mov_b32_e32 v8, v10
	v_mov_b32_e32 v9, v4
	v_pk_add_f32 v[18:19], v[12:13], v[18:19]
	v_pk_fma_f32 v[8:9], v[8:9], 0.5, v[28:29] op_sel_hi:[1,0,1] neg_lo:[0,0,1] neg_hi:[0,0,1]
	v_mov_b32_e32 v4, v11
	v_pk_fma_f32 v[4:5], v[4:5], 0.5, v[30:31] op_sel_hi:[1,0,1] neg_lo:[0,0,1] neg_hi:[0,0,1]
	v_pk_add_f32 v[14:15], v[14:15], v[20:21]
	s_waitcnt vmcnt(1)
	v_mov_b32_e32 v17, v2
	s_waitcnt vmcnt(0)
	v_mov_b32_e32 v12, v24
	v_mov_b32_e32 v13, v26
	v_pk_fma_f32 v[8:9], v[12:13], v[8:9], v[28:29]
	v_mov_b32_e32 v26, v25
	v_pk_fma_f32 v[10:11], v[26:27], v[4:5], v[30:31]
	v_and_b32_sdwa v5, v8, v207 dst_sel:DWORD dst_unused:UNUSED_PAD src0_sel:WORD_1 src1_sel:DWORD
	v_add3_u32 v12, v8, v5, s31
	v_and_b32_sdwa v5, v11, v207 dst_sel:DWORD dst_unused:UNUSED_PAD src0_sel:WORD_1 src1_sel:DWORD
	v_and_b32_sdwa v13, v10, v207 dst_sel:DWORD dst_unused:UNUSED_PAD src0_sel:WORD_1 src1_sel:DWORD
	v_and_b32_sdwa v4, v9, v207 dst_sel:DWORD dst_unused:UNUSED_PAD src0_sel:WORD_1 src1_sel:DWORD
	v_add3_u32 v5, v11, v5, s31
	v_add3_u32 v13, v10, v13, s31
	v_add3_u32 v4, v9, v4, s31
	v_and_b32_e32 v5, 0xffff0000, v5
	v_and_b32_e32 v13, 0xffff0000, v13
	v_or_b32_sdwa v5, v5, v4 dst_sel:DWORD dst_unused:UNUSED_PAD src0_sel:DWORD src1_sel:WORD_1
	v_or_b32_sdwa v4, v13, v12 dst_sel:DWORD dst_unused:UNUSED_PAD src0_sel:DWORD src1_sel:WORD_1
	v_mov_b32_e32 v13, v18
	v_mov_b32_e32 v18, v15
	v_mov_b32_e32 v12, v14
	v_pk_fma_f32 v[14:15], v[18:19], 0.5, v[6:7] op_sel_hi:[1,0,1] neg_lo:[0,0,1] neg_hi:[0,0,1]
	v_mov_b32_e32 v2, v1
	v_pk_fma_f32 v[12:13], v[12:13], 0.5, v[32:33] op_sel_hi:[1,0,1] neg_lo:[0,0,1] neg_hi:[0,0,1]
	v_mov_b32_e32 v16, v0
	v_pk_fma_f32 v[2:3], v[14:15], v[2:3], v[6:7]
	v_pk_fma_f32 v[12:13], v[12:13], v[16:17], v[32:33]
	v_and_b32_sdwa v6, v3, v207 dst_sel:DWORD dst_unused:UNUSED_PAD src0_sel:WORD_1 src1_sel:DWORD
	v_and_b32_sdwa v7, v2, v207 dst_sel:DWORD dst_unused:UNUSED_PAD src0_sel:WORD_1 src1_sel:DWORD
	v_and_b32_sdwa v0, v13, v207 dst_sel:DWORD dst_unused:UNUSED_PAD src0_sel:WORD_1 src1_sel:DWORD
	v_and_b32_sdwa v1, v12, v207 dst_sel:DWORD dst_unused:UNUSED_PAD src0_sel:WORD_1 src1_sel:DWORD
	v_add3_u32 v6, v3, v6, s31
	v_add3_u32 v7, v2, v7, s31
	v_add3_u32 v1, v12, v1, s31
	v_add3_u32 v0, v13, v0, s31
	v_and_b32_e32 v6, 0xffff0000, v6
	v_and_b32_e32 v14, 0xffff0000, v7
	v_or_b32_sdwa v7, v6, v0 dst_sel:DWORD dst_unused:UNUSED_PAD src0_sel:DWORD src1_sel:WORD_1
	v_or_b32_sdwa v6, v14, v1 dst_sel:DWORD dst_unused:UNUSED_PAD src0_sel:DWORD src1_sel:WORD_1
	v_mad_i64_i32 v[0:1], s[6:7], v22, s0, v[66:67]
	s_mov_b64 s[6:7], exec
	v_readlane_b32 s18, v255, 21
	v_readlane_b32 s19, v255, 22
	s_and_b64 s[18:19], s[6:7], s[18:19]
	s_xor_b64 s[52:53], s[18:19], s[6:7]
	s_mov_b64 exec, s[18:19]
	s_cbranch_execz .LBB0_571
	s_mov_b64 s[6:7], exec
	v_readlane_b32 s18, v255, 37
	v_readlane_b32 s19, v255, 38
	s_and_b64 s[18:19], s[6:7], s[18:19]
	s_xor_b64 s[56:57], s[18:19], s[6:7]
	s_mov_b64 exec, s[18:19]
	s_cbranch_execz .LBB0_568
; #define UFOR(v, n) _Pragma("unroll") for (int v = 0; v < (n); ++v)
; __device__ __forceinline__ void phase_features(KP p, int l) {
;     ...
;       else {
;         *(uint4*)(smem + F_KL + (tok * RW + ch) * 2) = pk;
;         float kc[8], kq[8]; ld8f(kk_ + ch, kc);
;         float ss = 0.f;
;         UFOR(x, 8) { kq[x] = o[x] * kc[x]; ss += kq[x] * kq[x]; }
;         ss += dppf<0xB1>(ss); ss += dppf<0x4E>(ss); ss += dppf<0x141>(ss);
;         const float inv = 1.f / fmaxf(sqrtf(ss), 1e-12f);
;         UFOR(x, 8) kq[x] *= inv;
;         const uint4 pq = pack8(kq);
;         *(uint4*)(FA(1) + go) = pq; *(uint4*)(smem + F_KK + (tok * RW + ch) * 2) = pq;
	v_add_u32_e32 v20, 0, v173
	ds_write_b128 v20, v[4:7] offset:8448
	global_load_dwordx4 v[4:7], v[76:77], off offset:16
	global_load_dwordx4 v[14:17], v[76:77], off
	s_mov_b32 s1, 0xf800000
	v_lshl_add_u64 v[0:1], v[0:1], 1, s[76:77]
	s_waitcnt vmcnt(0)
	v_mov_b32_e32 v18, v14
	v_mov_b32_e32 v19, v16
	v_mov_b32_e32 v16, v15
	v_pk_mul_f32 v[8:9], v[8:9], v[18:19]
	v_pk_mul_f32 v[10:11], v[10:11], v[16:17]
	v_mov_b32_e32 v16, v4
	v_mov_b32_e32 v17, v6
	v_mov_b32_e32 v14, v9
	v_mov_b32_e32 v15, v11
	v_pk_mul_f32 v[12:13], v[12:13], v[16:17]
	v_mov_b32_e32 v6, v5
	v_mul_f32_e32 v16, v8, v8
	v_pk_mul_f32 v[14:15], v[14:15], v[14:15]
	v_pk_mul_f32 v[2:3], v[2:3], v[6:7]
	v_fmac_f32_e32 v16, v10, v10
	v_mov_b32_e32 v4, v12
	v_mov_b32_e32 v5, v2
	v_add_f32_e32 v14, v16, v14
	v_pk_mul_f32 v[4:5], v[4:5], v[4:5]
	v_add_f32_e32 v14, v14, v15
	v_mov_b32_e32 v6, v13
	v_mov_b32_e32 v7, v3
	v_add_f32_e32 v4, v14, v4
	v_pk_mul_f32 v[6:7], v[6:7], v[6:7]
	v_add_f32_e32 v4, v4, v5
	v_add_f32_e32 v4, v4, v6
	v_add_f32_e32 v4, v4, v7
	s_nop 1
	v_add_f32_dpp v4, v4, v4 quad_perm:[1,0,3,2] row_mask:0xf bank_mask:0xf bound_ctrl:1
	s_nop 1
	v_add_f32_dpp v4, v4, v4 quad_perm:[2,3,0,1] row_mask:0xf bank_mask:0xf bound_ctrl:1
	s_nop 1
	v_add_f32_dpp v4, v4, v4 row_half_mirror row_mask:0xf bank_mask:0xf bound_ctrl:1
	v_cmp_gt_f32_e32 vcc, s1, v4
	v_mul_f32_e32 v5, 0x4f800000, v4
	s_nop 0
	v_cndmask_b32_e32 v4, v4, v5, vcc
	v_sqrt_f32_e32 v5, v4
	s_nop 0
	v_add_u32_e32 v6, -1, v5
	v_fma_f32 v7, -v6, v5, v4
	v_cmp_ge_f32_e64 s[84:85], 0, v7
	v_add_u32_e32 v7, 1, v5
	s_nop 0
	v_cndmask_b32_e64 v6, v5, v6, s[84:85]
	v_fma_f32 v5, -v7, v5, v4
	v_cmp_lt_f32_e64 s[84:85], 0, v5
	s_nop 1
	v_cndmask_b32_e64 v5, v6, v7, s[84:85]
	v_mul_f32_e32 v6, 0x37800000, v5
	v_cndmask_b32_e32 v5, v5, v6, vcc
	v_mov_b32_e32 v6, 0x260
	v_cmp_class_f32_e32 vcc, v4, v6
	s_nop 1
	v_cndmask_b32_e32 v4, v5, v4, vcc
	v_max_f32_e32 v4, 0x2b8cbccc, v4
	v_div_scale_f32 v5, s[6:7], v4, v4, 1.0
	v_rcp_f32_e32 v6, v5
	s_nop 0
	v_fma_f32 v7, -v5, v6, 1.0
	v_fmac_f32_e32 v6, v7, v6
	v_div_scale_f32 v7, vcc, 1.0, v4, 1.0
	v_mul_f32_e32 v14, v7, v6
	v_fma_f32 v15, -v5, v14, v7
	v_fmac_f32_e32 v14, v15, v6
	v_fma_f32 v5, -v5, v14, v7
	v_div_fmas_f32 v5, v5, v6, v14
	v_div_fixup_f32 v4, v5, v4, 1.0
	v_pk_mul_f32 v[6:7], v[8:9], v[4:5] op_sel_hi:[1,0]
	v_pk_mul_f32 v[8:9], v[10:11], v[4:5] op_sel_hi:[1,0]
	v_pk_mul_f32 v[10:11], v[12:13], v[4:5] op_sel_hi:[1,0]
	v_pk_mul_f32 v[4:5], v[2:3], v[4:5] op_sel_hi:[1,0]
	v_and_b32_sdwa v2, v7, v207 dst_sel:DWORD dst_unused:UNUSED_PAD src0_sel:WORD_1 src1_sel:DWORD
	v_and_b32_sdwa v3, v6, v207 dst_sel:DWORD dst_unused:UNUSED_PAD src0_sel:WORD_1 src1_sel:DWORD
	v_add3_u32 v6, v6, v3, s31
	v_add3_u32 v2, v7, v2, s31
	v_and_b32_sdwa v3, v9, v207 dst_sel:DWORD dst_unused:UNUSED_PAD src0_sel:WORD_1 src1_sel:DWORD
	v_and_b32_sdwa v7, v8, v207 dst_sel:DWORD dst_unused:UNUSED_PAD src0_sel:WORD_1 src1_sel:DWORD
	v_add3_u32 v3, v9, v3, s31
	v_add3_u32 v7, v8, v7, s31
	v_and_b32_e32 v3, 0xffff0000, v3
	v_and_b32_e32 v7, 0xffff0000, v7
	v_and_b32_sdwa v8, v5, v207 dst_sel:DWORD dst_unused:UNUSED_PAD src0_sel:WORD_1 src1_sel:DWORD
	v_and_b32_sdwa v9, v4, v207 dst_sel:DWORD dst_unused:UNUSED_PAD src0_sel:WORD_1 src1_sel:DWORD
	v_or_b32_sdwa v3, v3, v2 dst_sel:DWORD dst_unused:UNUSED_PAD src0_sel:DWORD src1_sel:WORD_1
	v_or_b32_sdwa v2, v7, v6 dst_sel:DWORD dst_unused:UNUSED_PAD src0_sel:DWORD src1_sel:WORD_1
	v_and_b32_sdwa v6, v11, v207 dst_sel:DWORD dst_unused:UNUSED_PAD src0_sel:WORD_1 src1_sel:DWORD
	v_and_b32_sdwa v7, v10, v207 dst_sel:DWORD dst_unused:UNUSED_PAD src0_sel:WORD_1 src1_sel:DWORD
	v_add3_u32 v5, v5, v8, s31
	v_add3_u32 v4, v4, v9, s31
	v_add3_u32 v7, v10, v7, s31
	v_add3_u32 v6, v11, v6, s31
	v_and_b32_e32 v5, 0xffff0000, v5
	v_and_b32_e32 v4, 0xffff0000, v4
	v_or_b32_sdwa v5, v5, v6 dst_sel:DWORD dst_unused:UNUSED_PAD src0_sel:DWORD src1_sel:WORD_1
	v_or_b32_sdwa v4, v4, v7 dst_sel:DWORD dst_unused:UNUSED_PAD src0_sel:DWORD src1_sel:WORD_1
	global_store_dwordx4 v[0:1], v[2:5], off
	ds_write_b128 v20, v[2:5] offset:33024

; #define UFOR(v, n) _Pragma("unroll") for (int v = 0; v < (n); ++v)
; __device__ __forceinline__ void phase_features(KP p, int l) {
;     ...
;       const int q = tid_ + 512 * i, tok = q / 288, grp = q % 288, sec = grp / 96, r = R0 + tok, col = grp * 8, ch = col - sec * RW;
;       const bool hm = r - 1 >= s0, hp = r + 1 < s0 + len;
;       const u16* z = zrw + (size_t)r * RWC + col;
;       float c[8], a[8], b[8], o[8], m[8];
;       unpack8(*(const uint4*)z, c);
;       if (hm) unpack8(*(const uint4*)(z - RWC), a); else UFOR(x, 8) a[x] = 0.f;
.LBB0_573:
	s_or_b64 exec, exec, s[52:53]
	v_add_u32_e32 v22, s15, v174
	s_movk_i32 s1, 0x1400
	v_mad_i64_i32 v[6:7], s[6:7], v22, s1, v[78:79]
	global_load_dwordx4 v[0:3], v[6:7], off
	v_cmp_lt_i32_e32 vcc, s38, v22
	v_mov_b32_e32 v14, 0
	v_mov_b32_e32 v15, 0
	v_mov_b32_e32 v16, 0
	v_mov_b32_e32 v17, 0
	v_mov_b32_e32 v212, 0
	v_mov_b32_e32 v213, 0
	v_mov_b32_e32 v214, 0
	v_mov_b32_e32 v215, 0
	s_and_saveexec_b64 s[52:53], vcc
	s_cbranch_execz .LBB0_575
	v_add_co_u32_e32 v4, vcc, 0xfffff000, v6
	s_nop 1
	v_addc_co_u32_e32 v5, vcc, -1, v7, vcc
	global_load_dwordx4 v[14:17], v[4:5], off offset:-1024

; #define UFOR(v, n) _Pragma("unroll") for (int v = 0; v < (n); ++v)
; __device__ __forceinline__ void phase_features(KP p, int l) {
;     ...
;       const bool hm = r - 1 >= s0, hp = r + 1 < s0 + len;
;       const u16* z = zrw + (size_t)r * RWC + col;
;       float c[8], a[8], b[8], o[8], m[8];
;       unpack8(*(const uint4*)z, c);
;       if (hm) unpack8(*(const uint4*)(z - RWC), a); else UFOR(x, 8) a[x] = 0.f;
;       if (hp) unpack8(*(const uint4*)(z + RWC), b); else UFOR(x, 8) b[x] = 0.f;
;       ld8f(mu + col, m);
;       UFOR(x, 8) o[x] = c[x] + (0.5f * (a[x] + b[x]) - c[x]) * m[x];
;       const uint4 pk = pack8(o);
;       const size_t go = (size_t)r * RW + ch;
;       if (sec == 0) { *(uint4*)(FA(0) + go) = pk; *(uint4*)(smem + F_RL + (tok * RW + ch) * 2) = pk; }
;       else if (sec == 2) { *(uint4*)(FA(2) + go) = pk; }
;       else {
;         *(uint4*)(smem + F_KL + (tok * RW + ch) * 2) = pk;
.LBB0_577:
	s_or_b64 exec, exec, s[52:53]
	s_waitcnt vmcnt(0)
	v_lshlrev_b32_e32 v10, 16, v14
	v_and_b32_e32 v11, 0xffff0000, v14
	v_lshlrev_b32_e32 v4, 16, v15
	v_and_b32_e32 v5, 0xffff0000, v15
	v_lshlrev_b32_e32 v14, 16, v16
	v_and_b32_e32 v15, 0xffff0000, v16
	v_lshlrev_b32_e32 v12, 16, v17
	v_and_b32_e32 v13, 0xffff0000, v17
	v_lshlrev_b32_e32 v8, 16, v212
	v_and_b32_e32 v9, 0xffff0000, v212
	v_lshlrev_b32_e32 v16, 16, v213
	v_and_b32_e32 v17, 0xffff0000, v213
	v_lshlrev_b32_e32 v20, 16, v214
	v_and_b32_e32 v21, 0xffff0000, v214
	v_lshlrev_b32_e32 v18, 16, v215
	v_and_b32_e32 v19, 0xffff0000, v215
	v_lshlrev_b32_e32 v29, 16, v1
	v_lshlrev_b32_e32 v28, 16, v0
	v_and_b32_e32 v31, 0xffff0000, v1
	v_and_b32_e32 v30, 0xffff0000, v0
	v_lshlrev_b32_e32 v33, 16, v3
	v_lshlrev_b32_e32 v32, 16, v2
	v_and_b32_e32 v7, 0xffff0000, v3
	v_and_b32_e32 v6, 0xffff0000, v2
	global_load_dwordx4 v[0:3], v[80:81], off offset:16
	global_load_dwordx4 v[24:27], v[80:81], off
	v_pk_add_f32 v[10:11], v[10:11], v[8:9]
	v_pk_add_f32 v[4:5], v[4:5], v[16:17]
	v_mov_b32_e32 v8, v10
	v_mov_b32_e32 v9, v4
	v_pk_add_f32 v[18:19], v[12:13], v[18:19]
	v_pk_fma_f32 v[8:9], v[8:9], 0.5, v[28:29] op_sel_hi:[1,0,1] neg_lo:[0,0,1] neg_hi:[0,0,1]
	v_mov_b32_e32 v4, v11
	v_pk_fma_f32 v[4:5], v[4:5], 0.5, v[30:31] op_sel_hi:[1,0,1] neg_lo:[0,0,1] neg_hi:[0,0,1]
	v_pk_add_f32 v[14:15], v[14:15], v[20:21]
	s_waitcnt vmcnt(1)
	v_mov_b32_e32 v17, v2
	s_waitcnt vmcnt(0)
	v_mov_b32_e32 v12, v24
	v_mov_b32_e32 v13, v26
	v_pk_fma_f32 v[8:9], v[12:13], v[8:9], v[28:29]
	v_mov_b32_e32 v26, v25
	v_pk_fma_f32 v[10:11], v[26:27], v[4:5], v[30:31]
	v_and_b32_sdwa v5, v8, v207 dst_sel:DWORD dst_unused:UNUSED_PAD src0_sel:WORD_1 src1_sel:DWORD
	v_add3_u32 v12, v8, v5, s31
	v_and_b32_sdwa v5, v11, v207 dst_sel:DWORD dst_unused:UNUSED_PAD src0_sel:WORD_1 src1_sel:DWORD
	v_and_b32_sdwa v13, v10, v207 dst_sel:DWORD dst_unused:UNUSED_PAD src0_sel:WORD_1 src1_sel:DWORD
	v_and_b32_sdwa v4, v9, v207 dst_sel:DWORD dst_unused:UNUSED_PAD src0_sel:WORD_1 src1_sel:DWORD
	v_add3_u32 v5, v11, v5, s31
	v_add3_u32 v13, v10, v13, s31
	v_add3_u32 v4, v9, v4, s31
	v_and_b32_e32 v5, 0xffff0000, v5
	v_and_b32_e32 v13, 0xffff0000, v13
	v_or_b32_sdwa v5, v5, v4 dst_sel:DWORD dst_unused:UNUSED_PAD src0_sel:DWORD src1_sel:WORD_1
	v_or_b32_sdwa v4, v13, v12 dst_sel:DWORD dst_unused:UNUSED_PAD src0_sel:DWORD src1_sel:WORD_1
	v_mov_b32_e32 v13, v18
	v_mov_b32_e32 v18, v15
	v_mov_b32_e32 v12, v14
	v_pk_fma_f32 v[14:15], v[18:19], 0.5, v[6:7] op_sel_hi:[1,0,1] neg_lo:[0,0,1] neg_hi:[0,0,1]
	v_mov_b32_e32 v2, v1
	v_pk_fma_f32 v[12:13], v[12:13], 0.5, v[32:33] op_sel_hi:[1,0,1] neg_lo:[0,0,1] neg_hi:[0,0,1]
	v_mov_b32_e32 v16, v0
	v_pk_fma_f32 v[2:3], v[14:15], v[2:3], v[6:7]
	v_pk_fma_f32 v[12:13], v[12:13], v[16:17], v[32:33]
	v_and_b32_sdwa v6, v3, v207 dst_sel:DWORD dst_unused:UNUSED_PAD src0_sel:WORD_1 src1_sel:DWORD
	v_and_b32_sdwa v7, v2, v207 dst_sel:DWORD dst_unused:UNUSED_PAD src0_sel:WORD_1 src1_sel:DWORD
	v_and_b32_sdwa v0, v13, v207 dst_sel:DWORD dst_unused:UNUSED_PAD src0_sel:WORD_1 src1_sel:DWORD
	v_and_b32_sdwa v1, v12, v207 dst_sel:DWORD dst_unused:UNUSED_PAD src0_sel:WORD_1 src1_sel:DWORD
	v_add3_u32 v6, v3, v6, s31
	v_add3_u32 v7, v2, v7, s31
	v_add3_u32 v1, v12, v1, s31
	v_add3_u32 v0, v13, v0, s31
	v_and_b32_e32 v6, 0xffff0000, v6
	v_and_b32_e32 v14, 0xffff0000, v7
	v_or_b32_sdwa v7, v6, v0 dst_sel:DWORD dst_unused:UNUSED_PAD src0_sel:DWORD src1_sel:WORD_1
	v_or_b32_sdwa v6, v14, v1 dst_sel:DWORD dst_unused:UNUSED_PAD src0_sel:DWORD src1_sel:WORD_1
	v_mad_i64_i32 v[0:1], s[6:7], v22, s0, v[84:85]
	s_mov_b64 s[6:7], exec
	v_readlane_b32 s18, v255, 27
	v_readlane_b32 s19, v255, 28
	s_and_b64 s[18:19], s[6:7], s[18:19]
	s_xor_b64 s[52:53], s[18:19], s[6:7]
	s_mov_b64 exec, s[18:19]
	s_cbranch_execz .LBB0_583
	s_mov_b64 s[6:7], exec
	v_readlane_b32 s18, v255, 39
	v_readlane_b32 s19, v255, 40
	s_and_b64 s[18:19], s[6:7], s[18:19]
	s_xor_b64 s[56:57], s[18:19], s[6:7]
	s_mov_b64 exec, s[18:19]
	s_cbranch_execz .LBB0_580
; #define UFOR(v, n) _Pragma("unroll") for (int v = 0; v < (n); ++v)
; __device__ __forceinline__ void phase_features(KP p, int l) {
;     ...
;       else {
;         *(uint4*)(smem + F_KL + (tok * RW + ch) * 2) = pk;
;         float kc[8], kq[8]; ld8f(kk_ + ch, kc);
;         float ss = 0.f;
;         UFOR(x, 8) { kq[x] = o[x] * kc[x]; ss += kq[x] * kq[x]; }
;         ss += dppf<0xB1>(ss); ss += dppf<0x4E>(ss); ss += dppf<0x141>(ss);
;         const float inv = 1.f / fmaxf(sqrtf(ss), 1e-12f);
;         UFOR(x, 8) kq[x] *= inv;
;         const uint4 pq = pack8(kq);
;         *(uint4*)(FA(1) + go) = pq; *(uint4*)(smem + F_KK + (tok * RW + ch) * 2) = pq;
	v_add_u32_e32 v20, 0, v176
	ds_write_b128 v20, v[4:7] offset:8448
	global_load_dwordx4 v[4:7], v[86:87], off offset:16
	global_load_dwordx4 v[14:17], v[86:87], off
	s_mov_b32 s1, 0xf800000
	v_lshl_add_u64 v[0:1], v[0:1], 1, s[76:77]
	s_waitcnt vmcnt(0)
	v_mov_b32_e32 v18, v14
	v_mov_b32_e32 v19, v16
	v_mov_b32_e32 v16, v15
	v_pk_mul_f32 v[8:9], v[8:9], v[18:19]
	v_pk_mul_f32 v[10:11], v[10:11], v[16:17]
	v_mov_b32_e32 v16, v4
	v_mov_b32_e32 v17, v6
	v_mov_b32_e32 v14, v9
	v_mov_b32_e32 v15, v11
	v_pk_mul_f32 v[12:13], v[12:13], v[16:17]
	v_mov_b32_e32 v6, v5
	v_mul_f32_e32 v16, v8, v8
	v_pk_mul_f32 v[14:15], v[14:15], v[14:15]
	v_pk_mul_f32 v[2:3], v[2:3], v[6:7]
	v_fmac_f32_e32 v16, v10, v10
	v_mov_b32_e32 v4, v12
	v_mov_b32_e32 v5, v2
	v_add_f32_e32 v14, v16, v14
	v_pk_mul_f32 v[4:5], v[4:5], v[4:5]
	v_add_f32_e32 v14, v14, v15
	v_mov_b32_e32 v6, v13
	v_mov_b32_e32 v7, v3
	v_add_f32_e32 v4, v14, v4
	v_pk_mul_f32 v[6:7], v[6:7], v[6:7]
	v_add_f32_e32 v4, v4, v5
	v_add_f32_e32 v4, v4, v6
	v_add_f32_e32 v4, v4, v7
	s_nop 1
	v_add_f32_dpp v4, v4, v4 quad_perm:[1,0,3,2] row_mask:0xf bank_mask:0xf bound_ctrl:1
	s_nop 1
	v_add_f32_dpp v4, v4, v4 quad_perm:[2,3,0,1] row_mask:0xf bank_mask:0xf bound_ctrl:1
	s_nop 1
	v_add_f32_dpp v4, v4, v4 row_half_mirror row_mask:0xf bank_mask:0xf bound_ctrl:1
	v_cmp_gt_f32_e32 vcc, s1, v4
	v_mul_f32_e32 v5, 0x4f800000, v4
	s_nop 0
	v_cndmask_b32_e32 v4, v4, v5, vcc
	v_sqrt_f32_e32 v5, v4
	s_nop 0
	v_add_u32_e32 v6, -1, v5
	v_fma_f32 v7, -v6, v5, v4
	v_cmp_ge_f32_e64 s[84:85], 0, v7
	v_add_u32_e32 v7, 1, v5
	s_nop 0
	v_cndmask_b32_e64 v6, v5, v6, s[84:85]
	v_fma_f32 v5, -v7, v5, v4
	v_cmp_lt_f32_e64 s[84:85], 0, v5
	s_nop 1
	v_cndmask_b32_e64 v5, v6, v7, s[84:85]
	v_mul_f32_e32 v6, 0x37800000, v5
	v_cndmask_b32_e32 v5, v5, v6, vcc
	v_mov_b32_e32 v6, 0x260
	v_cmp_class_f32_e32 vcc, v4, v6
	s_nop 1
	v_cndmask_b32_e32 v4, v5, v4, vcc
	v_max_f32_e32 v4, 0x2b8cbccc, v4
	v_div_scale_f32 v5, s[6:7], v4, v4, 1.0
	v_rcp_f32_e32 v6, v5
	s_nop 0
	v_fma_f32 v7, -v5, v6, 1.0
	v_fmac_f32_e32 v6, v7, v6
	v_div_scale_f32 v7, vcc, 1.0, v4, 1.0
	v_mul_f32_e32 v14, v7, v6
	v_fma_f32 v15, -v5, v14, v7
	v_fmac_f32_e32 v14, v15, v6
	v_fma_f32 v5, -v5, v14, v7
	v_div_fmas_f32 v5, v5, v6, v14
	v_div_fixup_f32 v4, v5, v4, 1.0
	v_pk_mul_f32 v[6:7], v[8:9], v[4:5] op_sel_hi:[1,0]
	v_pk_mul_f32 v[8:9], v[10:11], v[4:5] op_sel_hi:[1,0]
	v_pk_mul_f32 v[10:11], v[12:13], v[4:5] op_sel_hi:[1,0]
	v_pk_mul_f32 v[4:5], v[2:3], v[4:5] op_sel_hi:[1,0]
	v_and_b32_sdwa v2, v7, v207 dst_sel:DWORD dst_unused:UNUSED_PAD src0_sel:WORD_1 src1_sel:DWORD
	v_and_b32_sdwa v3, v6, v207 dst_sel:DWORD dst_unused:UNUSED_PAD src0_sel:WORD_1 src1_sel:DWORD
	v_add3_u32 v6, v6, v3, s31
	v_add3_u32 v2, v7, v2, s31
	v_and_b32_sdwa v3, v9, v207 dst_sel:DWORD dst_unused:UNUSED_PAD src0_sel:WORD_1 src1_sel:DWORD
	v_and_b32_sdwa v7, v8, v207 dst_sel:DWORD dst_unused:UNUSED_PAD src0_sel:WORD_1 src1_sel:DWORD
	v_add3_u32 v3, v9, v3, s31
	v_add3_u32 v7, v8, v7, s31
	v_and_b32_e32 v3, 0xffff0000, v3
	v_and_b32_e32 v7, 0xffff0000, v7
	v_and_b32_sdwa v8, v5, v207 dst_sel:DWORD dst_unused:UNUSED_PAD src0_sel:WORD_1 src1_sel:DWORD
	v_and_b32_sdwa v9, v4, v207 dst_sel:DWORD dst_unused:UNUSED_PAD src0_sel:WORD_1 src1_sel:DWORD
	v_or_b32_sdwa v3, v3, v2 dst_sel:DWORD dst_unused:UNUSED_PAD src0_sel:DWORD src1_sel:WORD_1
	v_or_b32_sdwa v2, v7, v6 dst_sel:DWORD dst_unused:UNUSED_PAD src0_sel:DWORD src1_sel:WORD_1
	v_and_b32_sdwa v6, v11, v207 dst_sel:DWORD dst_unused:UNUSED_PAD src0_sel:WORD_1 src1_sel:DWORD
	v_and_b32_sdwa v7, v10, v207 dst_sel:DWORD dst_unused:UNUSED_PAD src0_sel:WORD_1 src1_sel:DWORD
	v_add3_u32 v5, v5, v8, s31
	v_add3_u32 v4, v4, v9, s31
	v_add3_u32 v7, v10, v7, s31
	v_add3_u32 v6, v11, v6, s31
	v_and_b32_e32 v5, 0xffff0000, v5
	v_and_b32_e32 v4, 0xffff0000, v4
	v_or_b32_sdwa v5, v5, v6 dst_sel:DWORD dst_unused:UNUSED_PAD src0_sel:DWORD src1_sel:WORD_1
	v_or_b32_sdwa v4, v4, v7 dst_sel:DWORD dst_unused:UNUSED_PAD src0_sel:DWORD src1_sel:WORD_1
	global_store_dwordx4 v[0:1], v[2:5], off
	ds_write_b128 v20, v[2:5] offset:33024

; #define UFOR(v, n) _Pragma("unroll") for (int v = 0; v < (n); ++v)
; __device__ __forceinline__ void phase_features(KP p, int l) {
;     ...
;       const int q = tid_ + 512 * i, tok = q / 288, grp = q % 288, sec = grp / 96, r = R0 + tok, col = grp * 8, ch = col - sec * RW;
;       const bool hm = r - 1 >= s0, hp = r + 1 < s0 + len;
;       const u16* z = zrw + (size_t)r * RWC + col;
;       float c[8], a[8], b[8], o[8], m[8];
;       unpack8(*(const uint4*)z, c);
;       if (hm) unpack8(*(const uint4*)(z - RWC), a); else UFOR(x, 8) a[x] = 0.f;
.LBB0_585:
	s_or_b64 exec, exec, s[52:53]
	v_add_u32_e32 v22, s15, v175
	s_movk_i32 s1, 0x1400
	v_mad_i64_i32 v[6:7], s[6:7], v22, s1, v[88:89]
	global_load_dwordx4 v[0:3], v[6:7], off
	v_cmp_lt_i32_e32 vcc, s38, v22
	v_mov_b32_e32 v14, 0
	v_mov_b32_e32 v15, 0
	v_mov_b32_e32 v16, 0
	v_mov_b32_e32 v17, 0
	v_mov_b32_e32 v212, 0
	v_mov_b32_e32 v213, 0
	v_mov_b32_e32 v214, 0
	v_mov_b32_e32 v215, 0
	s_and_saveexec_b64 s[52:53], vcc
	s_cbranch_execz .LBB0_587
	v_add_co_u32_e32 v4, vcc, 0xfffff000, v6
	s_nop 1
	v_addc_co_u32_e32 v5, vcc, -1, v7, vcc
	global_load_dwordx4 v[14:17], v[4:5], off offset:-1024

; #define UFOR(v, n) _Pragma("unroll") for (int v = 0; v < (n); ++v)
; __device__ __forceinline__ void phase_features(KP p, int l) {
;     ...
;       const bool hm = r - 1 >= s0, hp = r + 1 < s0 + len;
;       const u16* z = zrw + (size_t)r * RWC + col;
;       float c[8], a[8], b[8], o[8], m[8];
;       unpack8(*(const uint4*)z, c);
;       if (hm) unpack8(*(const uint4*)(z - RWC), a); else UFOR(x, 8) a[x] = 0.f;
;       if (hp) unpack8(*(const uint4*)(z + RWC), b); else UFOR(x, 8) b[x] = 0.f;
;       ld8f(mu + col, m);
;       UFOR(x, 8) o[x] = c[x] + (0.5f * (a[x] + b[x]) - c[x]) * m[x];
;       const uint4 pk = pack8(o);
;       const size_t go = (size_t)r * RW + ch;
;       if (sec == 0) { *(uint4*)(FA(0) + go) = pk; *(uint4*)(smem + F_RL + (tok * RW + ch) * 2) = pk; }
;       else if (sec == 2) { *(uint4*)(FA(2) + go) = pk; }
;       else {
;         *(uint4*)(smem + F_KL + (tok * RW + ch) * 2) = pk;
.LBB0_589:
	s_or_b64 exec, exec, s[52:53]
	s_waitcnt vmcnt(0)
	v_lshlrev_b32_e32 v10, 16, v14
	v_and_b32_e32 v11, 0xffff0000, v14
	v_lshlrev_b32_e32 v4, 16, v15
	v_and_b32_e32 v5, 0xffff0000, v15
	v_lshlrev_b32_e32 v14, 16, v16
	v_and_b32_e32 v15, 0xffff0000, v16
	v_lshlrev_b32_e32 v12, 16, v17
	v_and_b32_e32 v13, 0xffff0000, v17
	v_lshlrev_b32_e32 v8, 16, v212
	v_and_b32_e32 v9, 0xffff0000, v212
	v_lshlrev_b32_e32 v16, 16, v213
	v_and_b32_e32 v17, 0xffff0000, v213
	v_lshlrev_b32_e32 v20, 16, v214
	v_and_b32_e32 v21, 0xffff0000, v214
	v_lshlrev_b32_e32 v18, 16, v215
	v_and_b32_e32 v19, 0xffff0000, v215
	v_lshlrev_b32_e32 v29, 16, v1
	v_lshlrev_b32_e32 v28, 16, v0
	v_and_b32_e32 v31, 0xffff0000, v1
	v_and_b32_e32 v30, 0xffff0000, v0
	v_lshlrev_b32_e32 v33, 16, v3
	v_lshlrev_b32_e32 v32, 16, v2
	v_and_b32_e32 v7, 0xffff0000, v3
	v_and_b32_e32 v6, 0xffff0000, v2
	global_load_dwordx4 v[0:3], v[90:91], off offset:16
	global_load_dwordx4 v[24:27], v[90:91], off
	v_pk_add_f32 v[10:11], v[10:11], v[8:9]
	v_pk_add_f32 v[4:5], v[4:5], v[16:17]
	v_mov_b32_e32 v8, v10
	v_mov_b32_e32 v9, v4
	v_pk_add_f32 v[18:19], v[12:13], v[18:19]
	v_pk_fma_f32 v[8:9], v[8:9], 0.5, v[28:29] op_sel_hi:[1,0,1] neg_lo:[0,0,1] neg_hi:[0,0,1]
	v_mov_b32_e32 v4, v11
	v_pk_fma_f32 v[4:5], v[4:5], 0.5, v[30:31] op_sel_hi:[1,0,1] neg_lo:[0,0,1] neg_hi:[0,0,1]
	v_pk_add_f32 v[14:15], v[14:15], v[20:21]
	s_waitcnt vmcnt(1)
	v_mov_b32_e32 v17, v2
	s_waitcnt vmcnt(0)
	v_mov_b32_e32 v12, v24
	v_mov_b32_e32 v13, v26
	v_pk_fma_f32 v[8:9], v[12:13], v[8:9], v[28:29]
	v_mov_b32_e32 v26, v25
	v_pk_fma_f32 v[10:11], v[26:27], v[4:5], v[30:31]
	v_and_b32_sdwa v5, v8, v207 dst_sel:DWORD dst_unused:UNUSED_PAD src0_sel:WORD_1 src1_sel:DWORD
	v_add3_u32 v12, v8, v5, s31
	v_and_b32_sdwa v5, v11, v207 dst_sel:DWORD dst_unused:UNUSED_PAD src0_sel:WORD_1 src1_sel:DWORD
	v_and_b32_sdwa v13, v10, v207 dst_sel:DWORD dst_unused:UNUSED_PAD src0_sel:WORD_1 src1_sel:DWORD
	v_and_b32_sdwa v4, v9, v207 dst_sel:DWORD dst_unused:UNUSED_PAD src0_sel:WORD_1 src1_sel:DWORD
	v_add3_u32 v5, v11, v5, s31
	v_add3_u32 v13, v10, v13, s31
	v_add3_u32 v4, v9, v4, s31
	v_and_b32_e32 v5, 0xffff0000, v5
	v_and_b32_e32 v13, 0xffff0000, v13
	v_or_b32_sdwa v5, v5, v4 dst_sel:DWORD dst_unused:UNUSED_PAD src0_sel:DWORD src1_sel:WORD_1
	v_or_b32_sdwa v4, v13, v12 dst_sel:DWORD dst_unused:UNUSED_PAD src0_sel:DWORD src1_sel:WORD_1
	v_mov_b32_e32 v13, v18
	v_mov_b32_e32 v18, v15
	v_mov_b32_e32 v12, v14
	v_pk_fma_f32 v[14:15], v[18:19], 0.5, v[6:7] op_sel_hi:[1,0,1] neg_lo:[0,0,1] neg_hi:[0,0,1]
	v_mov_b32_e32 v2, v1
	v_pk_fma_f32 v[12:13], v[12:13], 0.5, v[32:33] op_sel_hi:[1,0,1] neg_lo:[0,0,1] neg_hi:[0,0,1]
	v_mov_b32_e32 v16, v0
	v_pk_fma_f32 v[2:3], v[14:15], v[2:3], v[6:7]
	v_pk_fma_f32 v[12:13], v[12:13], v[16:17], v[32:33]
	v_and_b32_sdwa v6, v3, v207 dst_sel:DWORD dst_unused:UNUSED_PAD src0_sel:WORD_1 src1_sel:DWORD
	v_and_b32_sdwa v7, v2, v207 dst_sel:DWORD dst_unused:UNUSED_PAD src0_sel:WORD_1 src1_sel:DWORD
	v_and_b32_sdwa v0, v13, v207 dst_sel:DWORD dst_unused:UNUSED_PAD src0_sel:WORD_1 src1_sel:DWORD
	v_and_b32_sdwa v1, v12, v207 dst_sel:DWORD dst_unused:UNUSED_PAD src0_sel:WORD_1 src1_sel:DWORD
	v_add3_u32 v6, v3, v6, s31
	v_add3_u32 v7, v2, v7, s31
	v_add3_u32 v1, v12, v1, s31
	v_add3_u32 v0, v13, v0, s31
	v_and_b32_e32 v6, 0xffff0000, v6
	v_and_b32_e32 v14, 0xffff0000, v7
	v_or_b32_sdwa v7, v6, v0 dst_sel:DWORD dst_unused:UNUSED_PAD src0_sel:DWORD src1_sel:WORD_1
	v_or_b32_sdwa v6, v14, v1 dst_sel:DWORD dst_unused:UNUSED_PAD src0_sel:DWORD src1_sel:WORD_1
	v_mad_i64_i32 v[0:1], s[6:7], v22, s0, v[82:83]
	s_mov_b64 s[6:7], exec
	v_readlane_b32 s18, v255, 17
	v_readlane_b32 s19, v255, 18
	s_and_b64 s[18:19], s[6:7], s[18:19]
	s_xor_b64 s[52:53], s[18:19], s[6:7]
	s_mov_b64 exec, s[18:19]
	s_cbranch_execz .LBB0_595
	s_mov_b64 s[6:7], exec
	v_readlane_b32 s18, v255, 41
	v_readlane_b32 s19, v255, 42
	s_and_b64 s[18:19], s[6:7], s[18:19]
	s_xor_b64 s[56:57], s[18:19], s[6:7]
	s_mov_b64 exec, s[18:19]
	s_cbranch_execz .LBB0_592
; #define UFOR(v, n) _Pragma("unroll") for (int v = 0; v < (n); ++v)
; __device__ __forceinline__ void phase_features(KP p, int l) {
;     ...
;       else {
;         *(uint4*)(smem + F_KL + (tok * RW + ch) * 2) = pk;
;         float kc[8], kq[8]; ld8f(kk_ + ch, kc);
;         float ss = 0.f;
;         UFOR(x, 8) { kq[x] = o[x] * kc[x]; ss += kq[x] * kq[x]; }
;         ss += dppf<0xB1>(ss); ss += dppf<0x4E>(ss); ss += dppf<0x141>(ss);
;         const float inv = 1.f / fmaxf(sqrtf(ss), 1e-12f);
;         UFOR(x, 8) kq[x] *= inv;
;         const uint4 pq = pack8(kq);
;         *(uint4*)(FA(1) + go) = pq; *(uint4*)(smem + F_KK + (tok * RW + ch) * 2) = pq;
	v_add_u32_e32 v20, 0, v177
	ds_write_b128 v20, v[4:7] offset:8448
	global_load_dwordx4 v[4:7], v[98:99], off offset:16
	global_load_dwordx4 v[14:17], v[98:99], off
	s_mov_b32 s1, 0xf800000
	v_lshl_add_u64 v[0:1], v[0:1], 1, s[76:77]
	s_waitcnt vmcnt(0)
	v_mov_b32_e32 v18, v14
	v_mov_b32_e32 v19, v16
	v_mov_b32_e32 v16, v15
	v_pk_mul_f32 v[8:9], v[8:9], v[18:19]
	v_pk_mul_f32 v[10:11], v[10:11], v[16:17]
	v_mov_b32_e32 v16, v4
	v_mov_b32_e32 v17, v6
	v_mov_b32_e32 v14, v9
	v_mov_b32_e32 v15, v11
	v_pk_mul_f32 v[12:13], v[12:13], v[16:17]
	v_mov_b32_e32 v6, v5
	v_mul_f32_e32 v16, v8, v8
	v_pk_mul_f32 v[14:15], v[14:15], v[14:15]
	v_pk_mul_f32 v[2:3], v[2:3], v[6:7]
	v_fmac_f32_e32 v16, v10, v10
	v_mov_b32_e32 v4, v12
	v_mov_b32_e32 v5, v2
	v_add_f32_e32 v14, v16, v14
	v_pk_mul_f32 v[4:5], v[4:5], v[4:5]
	v_add_f32_e32 v14, v14, v15
	v_mov_b32_e32 v6, v13
	v_mov_b32_e32 v7, v3
	v_add_f32_e32 v4, v14, v4
	v_pk_mul_f32 v[6:7], v[6:7], v[6:7]
	v_add_f32_e32 v4, v4, v5
	v_add_f32_e32 v4, v4, v6
	v_add_f32_e32 v4, v4, v7
	s_nop 1
	v_add_f32_dpp v4, v4, v4 quad_perm:[1,0,3,2] row_mask:0xf bank_mask:0xf bound_ctrl:1
	s_nop 1
	v_add_f32_dpp v4, v4, v4 quad_perm:[2,3,0,1] row_mask:0xf bank_mask:0xf bound_ctrl:1
	s_nop 1
	v_add_f32_dpp v4, v4, v4 row_half_mirror row_mask:0xf bank_mask:0xf bound_ctrl:1
	v_cmp_gt_f32_e32 vcc, s1, v4
	v_mul_f32_e32 v5, 0x4f800000, v4
	s_nop 0
	v_cndmask_b32_e32 v4, v4, v5, vcc
	v_sqrt_f32_e32 v5, v4
	s_nop 0
	v_add_u32_e32 v6, -1, v5
	v_fma_f32 v7, -v6, v5, v4
	v_cmp_ge_f32_e64 s[84:85], 0, v7
	v_add_u32_e32 v7, 1, v5
	s_nop 0
	v_cndmask_b32_e64 v6, v5, v6, s[84:85]
	v_fma_f32 v5, -v7, v5, v4
	v_cmp_lt_f32_e64 s[84:85], 0, v5
	s_nop 1
	v_cndmask_b32_e64 v5, v6, v7, s[84:85]
	v_mul_f32_e32 v6, 0x37800000, v5
	v_cndmask_b32_e32 v5, v5, v6, vcc
	v_mov_b32_e32 v6, 0x260
	v_cmp_class_f32_e32 vcc, v4, v6
	s_nop 1
	v_cndmask_b32_e32 v4, v5, v4, vcc
	v_max_f32_e32 v4, 0x2b8cbccc, v4
	v_div_scale_f32 v5, s[6:7], v4, v4, 1.0
	v_rcp_f32_e32 v6, v5
	s_nop 0
	v_fma_f32 v7, -v5, v6, 1.0
	v_fmac_f32_e32 v6, v7, v6
	v_div_scale_f32 v7, vcc, 1.0, v4, 1.0
	v_mul_f32_e32 v14, v7, v6
	v_fma_f32 v15, -v5, v14, v7
	v_fmac_f32_e32 v14, v15, v6
	v_fma_f32 v5, -v5, v14, v7
	v_div_fmas_f32 v5, v5, v6, v14
	v_div_fixup_f32 v4, v5, v4, 1.0
	v_pk_mul_f32 v[6:7], v[8:9], v[4:5] op_sel_hi:[1,0]
	v_pk_mul_f32 v[8:9], v[10:11], v[4:5] op_sel_hi:[1,0]
	v_pk_mul_f32 v[10:11], v[12:13], v[4:5] op_sel_hi:[1,0]
	v_pk_mul_f32 v[4:5], v[2:3], v[4:5] op_sel_hi:[1,0]
	v_and_b32_sdwa v2, v7, v207 dst_sel:DWORD dst_unused:UNUSED_PAD src0_sel:WORD_1 src1_sel:DWORD
	v_and_b32_sdwa v3, v6, v207 dst_sel:DWORD dst_unused:UNUSED_PAD src0_sel:WORD_1 src1_sel:DWORD
	v_add3_u32 v6, v6, v3, s31
	v_add3_u32 v2, v7, v2, s31
	v_and_b32_sdwa v3, v9, v207 dst_sel:DWORD dst_unused:UNUSED_PAD src0_sel:WORD_1 src1_sel:DWORD
	v_and_b32_sdwa v7, v8, v207 dst_sel:DWORD dst_unused:UNUSED_PAD src0_sel:WORD_1 src1_sel:DWORD
	v_add3_u32 v3, v9, v3, s31
	v_add3_u32 v7, v8, v7, s31
	v_and_b32_e32 v3, 0xffff0000, v3
	v_and_b32_e32 v7, 0xffff0000, v7
	v_and_b32_sdwa v8, v5, v207 dst_sel:DWORD dst_unused:UNUSED_PAD src0_sel:WORD_1 src1_sel:DWORD
	v_and_b32_sdwa v9, v4, v207 dst_sel:DWORD dst_unused:UNUSED_PAD src0_sel:WORD_1 src1_sel:DWORD
	v_or_b32_sdwa v3, v3, v2 dst_sel:DWORD dst_unused:UNUSED_PAD src0_sel:DWORD src1_sel:WORD_1
	v_or_b32_sdwa v2, v7, v6 dst_sel:DWORD dst_unused:UNUSED_PAD src0_sel:DWORD src1_sel:WORD_1
	v_and_b32_sdwa v6, v11, v207 dst_sel:DWORD dst_unused:UNUSED_PAD src0_sel:WORD_1 src1_sel:DWORD
	v_and_b32_sdwa v7, v10, v207 dst_sel:DWORD dst_unused:UNUSED_PAD src0_sel:WORD_1 src1_sel:DWORD
	v_add3_u32 v5, v5, v8, s31
	v_add3_u32 v4, v4, v9, s31
	v_add3_u32 v7, v10, v7, s31
	v_add3_u32 v6, v11, v6, s31
	v_and_b32_e32 v5, 0xffff0000, v5
	v_and_b32_e32 v4, 0xffff0000, v4
	v_or_b32_sdwa v5, v5, v6 dst_sel:DWORD dst_unused:UNUSED_PAD src0_sel:DWORD src1_sel:WORD_1
	v_or_b32_sdwa v4, v4, v7 dst_sel:DWORD dst_unused:UNUSED_PAD src0_sel:DWORD src1_sel:WORD_1
	global_store_dwordx4 v[0:1], v[2:5], off
	ds_write_b128 v20, v[2:5] offset:33024

; #define UFOR(v, n) _Pragma("unroll") for (int v = 0; v < (n); ++v)
; __device__ __forceinline__ void phase_features(KP p, int l) {
;     ...
;       const int q = tid_ + 512 * i, tok = q / 288, grp = q % 288, sec = grp / 96, r = R0 + tok, col = grp * 8, ch = col - sec * RW;
;       const bool hm = r - 1 >= s0, hp = r + 1 < s0 + len;
;       const u16* z = zrw + (size_t)r * RWC + col;
;       float c[8], a[8], b[8], o[8], m[8];
;       unpack8(*(const uint4*)z, c);
;       if (hm) unpack8(*(const uint4*)(z - RWC), a); else UFOR(x, 8) a[x] = 0.f;
.LBB0_597:
	s_or_b64 exec, exec, s[52:53]
	v_add_u32_e32 v22, s15, v178
	s_movk_i32 s1, 0x1400
	v_mad_i64_i32 v[6:7], s[6:7], v22, s1, v[100:101]
	global_load_dwordx4 v[0:3], v[6:7], off
	v_cmp_lt_i32_e32 vcc, s38, v22
	v_mov_b32_e32 v14, 0
	v_mov_b32_e32 v15, 0
	v_mov_b32_e32 v16, 0
	v_mov_b32_e32 v17, 0
	v_mov_b32_e32 v212, 0
	v_mov_b32_e32 v213, 0
	v_mov_b32_e32 v214, 0
	v_mov_b32_e32 v215, 0
	s_and_saveexec_b64 s[52:53], vcc
	s_cbranch_execz .LBB0_599
	v_add_co_u32_e32 v4, vcc, 0xfffff000, v6
	s_nop 1
	v_addc_co_u32_e32 v5, vcc, -1, v7, vcc
	global_load_dwordx4 v[14:17], v[4:5], off offset:-1024

; #define UFOR(v, n) _Pragma("unroll") for (int v = 0; v < (n); ++v)
; __device__ __forceinline__ void phase_features(KP p, int l) {
;     ...
;       const bool hm = r - 1 >= s0, hp = r + 1 < s0 + len;
;       const u16* z = zrw + (size_t)r * RWC + col;
;       float c[8], a[8], b[8], o[8], m[8];
;       unpack8(*(const uint4*)z, c);
;       if (hm) unpack8(*(const uint4*)(z - RWC), a); else UFOR(x, 8) a[x] = 0.f;
;       if (hp) unpack8(*(const uint4*)(z + RWC), b); else UFOR(x, 8) b[x] = 0.f;
;       ld8f(mu + col, m);
;       UFOR(x, 8) o[x] = c[x] + (0.5f * (a[x] + b[x]) - c[x]) * m[x];
;       const uint4 pk = pack8(o);
;       const size_t go = (size_t)r * RW + ch;
;       if (sec == 0) { *(uint4*)(FA(0) + go) = pk; *(uint4*)(smem + F_RL + (tok * RW + ch) * 2) = pk; }
;       else if (sec == 2) { *(uint4*)(FA(2) + go) = pk; }
;       else {
;         *(uint4*)(smem + F_KL + (tok * RW + ch) * 2) = pk;
.LBB0_601:
	s_or_b64 exec, exec, s[52:53]
	s_waitcnt vmcnt(0)
	v_lshlrev_b32_e32 v10, 16, v14
	v_and_b32_e32 v11, 0xffff0000, v14
	v_lshlrev_b32_e32 v4, 16, v15
	v_and_b32_e32 v5, 0xffff0000, v15
	v_lshlrev_b32_e32 v14, 16, v16
	v_and_b32_e32 v15, 0xffff0000, v16
	v_lshlrev_b32_e32 v12, 16, v17
	v_and_b32_e32 v13, 0xffff0000, v17
	v_lshlrev_b32_e32 v8, 16, v212
	v_and_b32_e32 v9, 0xffff0000, v212
	v_lshlrev_b32_e32 v16, 16, v213
	v_and_b32_e32 v17, 0xffff0000, v213
	v_lshlrev_b32_e32 v20, 16, v214
	v_and_b32_e32 v21, 0xffff0000, v214
	v_lshlrev_b32_e32 v18, 16, v215
	v_and_b32_e32 v19, 0xffff0000, v215
	v_lshlrev_b32_e32 v29, 16, v1
	v_lshlrev_b32_e32 v28, 16, v0
	v_and_b32_e32 v31, 0xffff0000, v1
	v_and_b32_e32 v30, 0xffff0000, v0
	v_lshlrev_b32_e32 v33, 16, v3
	v_lshlrev_b32_e32 v32, 16, v2
	v_and_b32_e32 v7, 0xffff0000, v3
	v_and_b32_e32 v6, 0xffff0000, v2
	global_load_dwordx4 v[0:3], v[92:93], off offset:16
	global_load_dwordx4 v[24:27], v[92:93], off
	v_pk_add_f32 v[10:11], v[10:11], v[8:9]
	v_pk_add_f32 v[4:5], v[4:5], v[16:17]
	v_mov_b32_e32 v8, v10
	v_mov_b32_e32 v9, v4
	v_pk_add_f32 v[18:19], v[12:13], v[18:19]
	v_pk_fma_f32 v[8:9], v[8:9], 0.5, v[28:29] op_sel_hi:[1,0,1] neg_lo:[0,0,1] neg_hi:[0,0,1]
	v_mov_b32_e32 v4, v11
	v_pk_fma_f32 v[4:5], v[4:5], 0.5, v[30:31] op_sel_hi:[1,0,1] neg_lo:[0,0,1] neg_hi:[0,0,1]
	v_pk_add_f32 v[14:15], v[14:15], v[20:21]
	s_waitcnt vmcnt(1)
	v_mov_b32_e32 v17, v2
	s_waitcnt vmcnt(0)
	v_mov_b32_e32 v12, v24
	v_mov_b32_e32 v13, v26
	v_pk_fma_f32 v[8:9], v[12:13], v[8:9], v[28:29]
	v_mov_b32_e32 v26, v25
	v_pk_fma_f32 v[10:11], v[26:27], v[4:5], v[30:31]
	v_and_b32_sdwa v5, v8, v207 dst_sel:DWORD dst_unused:UNUSED_PAD src0_sel:WORD_1 src1_sel:DWORD
	v_add3_u32 v12, v8, v5, s31
	v_and_b32_sdwa v5, v11, v207 dst_sel:DWORD dst_unused:UNUSED_PAD src0_sel:WORD_1 src1_sel:DWORD
	v_and_b32_sdwa v13, v10, v207 dst_sel:DWORD dst_unused:UNUSED_PAD src0_sel:WORD_1 src1_sel:DWORD
	v_and_b32_sdwa v4, v9, v207 dst_sel:DWORD dst_unused:UNUSED_PAD src0_sel:WORD_1 src1_sel:DWORD
	v_add3_u32 v5, v11, v5, s31
	v_add3_u32 v13, v10, v13, s31
	v_add3_u32 v4, v9, v4, s31
	v_and_b32_e32 v5, 0xffff0000, v5
	v_and_b32_e32 v13, 0xffff0000, v13
	v_or_b32_sdwa v5, v5, v4 dst_sel:DWORD dst_unused:UNUSED_PAD src0_sel:DWORD src1_sel:WORD_1
	v_or_b32_sdwa v4, v13, v12 dst_sel:DWORD dst_unused:UNUSED_PAD src0_sel:DWORD src1_sel:WORD_1
	v_mov_b32_e32 v13, v18
	v_mov_b32_e32 v18, v15
	v_mov_b32_e32 v12, v14
	v_pk_fma_f32 v[14:15], v[18:19], 0.5, v[6:7] op_sel_hi:[1,0,1] neg_lo:[0,0,1] neg_hi:[0,0,1]
	v_mov_b32_e32 v2, v1
	v_pk_fma_f32 v[12:13], v[12:13], 0.5, v[32:33] op_sel_hi:[1,0,1] neg_lo:[0,0,1] neg_hi:[0,0,1]
	v_mov_b32_e32 v16, v0
	v_pk_fma_f32 v[2:3], v[14:15], v[2:3], v[6:7]
	v_pk_fma_f32 v[12:13], v[12:13], v[16:17], v[32:33]
	v_and_b32_sdwa v6, v3, v207 dst_sel:DWORD dst_unused:UNUSED_PAD src0_sel:WORD_1 src1_sel:DWORD
	v_and_b32_sdwa v7, v2, v207 dst_sel:DWORD dst_unused:UNUSED_PAD src0_sel:WORD_1 src1_sel:DWORD
	v_and_b32_sdwa v0, v13, v207 dst_sel:DWORD dst_unused:UNUSED_PAD src0_sel:WORD_1 src1_sel:DWORD
	v_and_b32_sdwa v1, v12, v207 dst_sel:DWORD dst_unused:UNUSED_PAD src0_sel:WORD_1 src1_sel:DWORD
	v_add3_u32 v6, v3, v6, s31
	v_add3_u32 v7, v2, v7, s31
	v_add3_u32 v1, v12, v1, s31
	v_add3_u32 v0, v13, v0, s31
	v_and_b32_e32 v6, 0xffff0000, v6
	v_and_b32_e32 v14, 0xffff0000, v7
	v_or_b32_sdwa v7, v6, v0 dst_sel:DWORD dst_unused:UNUSED_PAD src0_sel:DWORD src1_sel:WORD_1
	v_or_b32_sdwa v6, v14, v1 dst_sel:DWORD dst_unused:UNUSED_PAD src0_sel:DWORD src1_sel:WORD_1
	v_mad_i64_i32 v[0:1], s[6:7], v22, s0, v[104:105]
	s_mov_b64 s[6:7], exec
	v_readlane_b32 s18, v255, 43
	v_readlane_b32 s19, v255, 44
	s_and_b64 s[18:19], s[6:7], s[18:19]
	s_xor_b64 s[52:53], s[18:19], s[6:7]
	s_mov_b64 exec, s[18:19]
	s_cbranch_execz .LBB0_607
	s_mov_b64 s[6:7], exec
	v_readlane_b32 s18, v255, 45
	v_readlane_b32 s19, v255, 46
	s_and_b64 s[18:19], s[6:7], s[18:19]
	s_xor_b64 s[56:57], s[18:19], s[6:7]
	s_mov_b64 exec, s[18:19]
	s_cbranch_execz .LBB0_604
; #define UFOR(v, n) _Pragma("unroll") for (int v = 0; v < (n); ++v)
; __device__ __forceinline__ void phase_features(KP p, int l) {
;     ...
;       else {
;         *(uint4*)(smem + F_KL + (tok * RW + ch) * 2) = pk;
;         float kc[8], kq[8]; ld8f(kk_ + ch, kc);
;         float ss = 0.f;
;         UFOR(x, 8) { kq[x] = o[x] * kc[x]; ss += kq[x] * kq[x]; }
;         ss += dppf<0xB1>(ss); ss += dppf<0x4E>(ss); ss += dppf<0x141>(ss);
;         const float inv = 1.f / fmaxf(sqrtf(ss), 1e-12f);
;         UFOR(x, 8) kq[x] *= inv;
;         const uint4 pq = pack8(kq);
;         *(uint4*)(FA(1) + go) = pq; *(uint4*)(smem + F_KK + (tok * RW + ch) * 2) = pq;
	v_add_u32_e32 v20, 0, v181
	ds_write_b128 v20, v[4:7] offset:8448
	global_load_dwordx4 v[4:7], v[106:107], off offset:16
	global_load_dwordx4 v[14:17], v[106:107], off
	s_mov_b32 s1, 0xf800000
	v_lshl_add_u64 v[0:1], v[0:1], 1, s[76:77]
	s_waitcnt vmcnt(0)
	v_mov_b32_e32 v18, v14
	v_mov_b32_e32 v19, v16
	v_mov_b32_e32 v16, v15
	v_pk_mul_f32 v[8:9], v[8:9], v[18:19]
	v_pk_mul_f32 v[10:11], v[10:11], v[16:17]
	v_mov_b32_e32 v16, v4
	v_mov_b32_e32 v17, v6
	v_mov_b32_e32 v14, v9
	v_mov_b32_e32 v15, v11
	v_pk_mul_f32 v[12:13], v[12:13], v[16:17]
	v_mov_b32_e32 v6, v5
	v_mul_f32_e32 v16, v8, v8
	v_pk_mul_f32 v[14:15], v[14:15], v[14:15]
	v_pk_mul_f32 v[2:3], v[2:3], v[6:7]
	v_fmac_f32_e32 v16, v10, v10
	v_mov_b32_e32 v4, v12
	v_mov_b32_e32 v5, v2
	v_add_f32_e32 v14, v16, v14
	v_pk_mul_f32 v[4:5], v[4:5], v[4:5]
	v_add_f32_e32 v14, v14, v15
	v_mov_b32_e32 v6, v13
	v_mov_b32_e32 v7, v3
	v_add_f32_e32 v4, v14, v4
	v_pk_mul_f32 v[6:7], v[6:7], v[6:7]
	v_add_f32_e32 v4, v4, v5
	v_add_f32_e32 v4, v4, v6
	v_add_f32_e32 v4, v4, v7
	s_nop 1
	v_add_f32_dpp v4, v4, v4 quad_perm:[1,0,3,2] row_mask:0xf bank_mask:0xf bound_ctrl:1
	s_nop 1
	v_add_f32_dpp v4, v4, v4 quad_perm:[2,3,0,1] row_mask:0xf bank_mask:0xf bound_ctrl:1
	s_nop 1
	v_add_f32_dpp v4, v4, v4 row_half_mirror row_mask:0xf bank_mask:0xf bound_ctrl:1
	v_cmp_gt_f32_e32 vcc, s1, v4
	v_mul_f32_e32 v5, 0x4f800000, v4
	s_nop 0
	v_cndmask_b32_e32 v4, v4, v5, vcc
	v_sqrt_f32_e32 v5, v4
	s_nop 0
	v_add_u32_e32 v6, -1, v5
	v_fma_f32 v7, -v6, v5, v4
	v_cmp_ge_f32_e64 s[84:85], 0, v7
	v_add_u32_e32 v7, 1, v5
	s_nop 0
	v_cndmask_b32_e64 v6, v5, v6, s[84:85]
	v_fma_f32 v5, -v7, v5, v4
	v_cmp_lt_f32_e64 s[84:85], 0, v5
	s_nop 1
	v_cndmask_b32_e64 v5, v6, v7, s[84:85]
	v_mul_f32_e32 v6, 0x37800000, v5
	v_cndmask_b32_e32 v5, v5, v6, vcc
	v_mov_b32_e32 v6, 0x260
	v_cmp_class_f32_e32 vcc, v4, v6
	s_nop 1
	v_cndmask_b32_e32 v4, v5, v4, vcc
	v_max_f32_e32 v4, 0x2b8cbccc, v4
	v_div_scale_f32 v5, s[6:7], v4, v4, 1.0
	v_rcp_f32_e32 v6, v5
	s_nop 0
	v_fma_f32 v7, -v5, v6, 1.0
	v_fmac_f32_e32 v6, v7, v6
	v_div_scale_f32 v7, vcc, 1.0, v4, 1.0
	v_mul_f32_e32 v14, v7, v6
	v_fma_f32 v15, -v5, v14, v7
	v_fmac_f32_e32 v14, v15, v6
	v_fma_f32 v5, -v5, v14, v7
	v_div_fmas_f32 v5, v5, v6, v14
	v_div_fixup_f32 v4, v5, v4, 1.0
	v_pk_mul_f32 v[6:7], v[8:9], v[4:5] op_sel_hi:[1,0]
	v_pk_mul_f32 v[8:9], v[10:11], v[4:5] op_sel_hi:[1,0]
	v_pk_mul_f32 v[10:11], v[12:13], v[4:5] op_sel_hi:[1,0]
	v_pk_mul_f32 v[4:5], v[2:3], v[4:5] op_sel_hi:[1,0]
	v_and_b32_sdwa v2, v7, v207 dst_sel:DWORD dst_unused:UNUSED_PAD src0_sel:WORD_1 src1_sel:DWORD
	v_and_b32_sdwa v3, v6, v207 dst_sel:DWORD dst_unused:UNUSED_PAD src0_sel:WORD_1 src1_sel:DWORD
	v_add3_u32 v6, v6, v3, s31
	v_add3_u32 v2, v7, v2, s31
	v_and_b32_sdwa v3, v9, v207 dst_sel:DWORD dst_unused:UNUSED_PAD src0_sel:WORD_1 src1_sel:DWORD
	v_and_b32_sdwa v7, v8, v207 dst_sel:DWORD dst_unused:UNUSED_PAD src0_sel:WORD_1 src1_sel:DWORD
	v_add3_u32 v3, v9, v3, s31
	v_add3_u32 v7, v8, v7, s31
	v_and_b32_e32 v3, 0xffff0000, v3
	v_and_b32_e32 v7, 0xffff0000, v7
	v_and_b32_sdwa v8, v5, v207 dst_sel:DWORD dst_unused:UNUSED_PAD src0_sel:WORD_1 src1_sel:DWORD
	v_and_b32_sdwa v9, v4, v207 dst_sel:DWORD dst_unused:UNUSED_PAD src0_sel:WORD_1 src1_sel:DWORD
	v_or_b32_sdwa v3, v3, v2 dst_sel:DWORD dst_unused:UNUSED_PAD src0_sel:DWORD src1_sel:WORD_1
	v_or_b32_sdwa v2, v7, v6 dst_sel:DWORD dst_unused:UNUSED_PAD src0_sel:DWORD src1_sel:WORD_1
	v_and_b32_sdwa v6, v11, v207 dst_sel:DWORD dst_unused:UNUSED_PAD src0_sel:WORD_1 src1_sel:DWORD
	v_and_b32_sdwa v7, v10, v207 dst_sel:DWORD dst_unused:UNUSED_PAD src0_sel:WORD_1 src1_sel:DWORD
	v_add3_u32 v5, v5, v8, s31
	v_add3_u32 v4, v4, v9, s31
	v_add3_u32 v7, v10, v7, s31
	v_add3_u32 v6, v11, v6, s31
	v_and_b32_e32 v5, 0xffff0000, v5
	v_and_b32_e32 v4, 0xffff0000, v4
	v_or_b32_sdwa v5, v5, v6 dst_sel:DWORD dst_unused:UNUSED_PAD src0_sel:DWORD src1_sel:WORD_1
	v_or_b32_sdwa v4, v4, v7 dst_sel:DWORD dst_unused:UNUSED_PAD src0_sel:DWORD src1_sel:WORD_1
	global_store_dwordx4 v[0:1], v[2:5], off
	ds_write_b128 v20, v[2:5] offset:33024

; #define UFOR(v, n) _Pragma("unroll") for (int v = 0; v < (n); ++v)
; __device__ __forceinline__ void phase_features(KP p, int l) {
;     ...
;       const int q = tid_ + 512 * i, tok = q / 288, grp = q % 288, sec = grp / 96, r = R0 + tok, col = grp * 8, ch = col - sec * RW;
;       const bool hm = r - 1 >= s0, hp = r + 1 < s0 + len;
;       const u16* z = zrw + (size_t)r * RWC + col;
;       float c[8], a[8], b[8], o[8], m[8];
;       unpack8(*(const uint4*)z, c);
;       if (hm) unpack8(*(const uint4*)(z - RWC), a); else UFOR(x, 8) a[x] = 0.f;
.LBB0_609:
	s_or_b64 exec, exec, s[52:53]
	v_add_u32_e32 v22, s15, v179
	s_movk_i32 s1, 0x1400
	v_mad_i64_i32 v[6:7], s[6:7], v22, s1, v[114:115]
	global_load_dwordx4 v[0:3], v[6:7], off
	v_cmp_lt_i32_e32 vcc, s38, v22
	v_mov_b32_e32 v14, 0
	v_mov_b32_e32 v15, 0
	v_mov_b32_e32 v16, 0
	v_mov_b32_e32 v17, 0
	v_mov_b32_e32 v212, 0
	v_mov_b32_e32 v213, 0
	v_mov_b32_e32 v214, 0
	v_mov_b32_e32 v215, 0
	s_and_saveexec_b64 s[52:53], vcc
	s_cbranch_execz .LBB0_611
	v_add_co_u32_e32 v4, vcc, 0xfffff000, v6
	s_nop 1
	v_addc_co_u32_e32 v5, vcc, -1, v7, vcc
	global_load_dwordx4 v[14:17], v[4:5], off offset:-1024

; #define UFOR(v, n) _Pragma("unroll") for (int v = 0; v < (n); ++v)
; __device__ __forceinline__ void phase_features(KP p, int l) {
;     ...
;       const bool hm = r - 1 >= s0, hp = r + 1 < s0 + len;
;       const u16* z = zrw + (size_t)r * RWC + col;
;       float c[8], a[8], b[8], o[8], m[8];
;       unpack8(*(const uint4*)z, c);
;       if (hm) unpack8(*(const uint4*)(z - RWC), a); else UFOR(x, 8) a[x] = 0.f;
;       if (hp) unpack8(*(const uint4*)(z + RWC), b); else UFOR(x, 8) b[x] = 0.f;
;       ld8f(mu + col, m);
;       UFOR(x, 8) o[x] = c[x] + (0.5f * (a[x] + b[x]) - c[x]) * m[x];
;       const uint4 pk = pack8(o);
;       const size_t go = (size_t)r * RW + ch;
;       if (sec == 0) { *(uint4*)(FA(0) + go) = pk; *(uint4*)(smem + F_RL + (tok * RW + ch) * 2) = pk; }
;       else if (sec == 2) { *(uint4*)(FA(2) + go) = pk; }
;       else {
;         *(uint4*)(smem + F_KL + (tok * RW + ch) * 2) = pk;
.LBB0_613:
	s_or_b64 exec, exec, s[52:53]
	s_waitcnt vmcnt(0)
	v_lshlrev_b32_e32 v10, 16, v14
	v_and_b32_e32 v11, 0xffff0000, v14
	v_lshlrev_b32_e32 v4, 16, v15
	v_and_b32_e32 v5, 0xffff0000, v15
	v_lshlrev_b32_e32 v14, 16, v16
	v_and_b32_e32 v15, 0xffff0000, v16
	v_lshlrev_b32_e32 v12, 16, v17
	v_and_b32_e32 v13, 0xffff0000, v17
	v_lshlrev_b32_e32 v8, 16, v212
	v_and_b32_e32 v9, 0xffff0000, v212
	v_lshlrev_b32_e32 v16, 16, v213
	v_and_b32_e32 v17, 0xffff0000, v213
	v_lshlrev_b32_e32 v20, 16, v214
	v_and_b32_e32 v21, 0xffff0000, v214
	v_lshlrev_b32_e32 v18, 16, v215
	v_and_b32_e32 v19, 0xffff0000, v215
	v_lshlrev_b32_e32 v29, 16, v1
	v_lshlrev_b32_e32 v28, 16, v0
	v_and_b32_e32 v31, 0xffff0000, v1
	v_and_b32_e32 v30, 0xffff0000, v0
	v_lshlrev_b32_e32 v33, 16, v3
	v_lshlrev_b32_e32 v32, 16, v2
	v_and_b32_e32 v7, 0xffff0000, v3
	v_and_b32_e32 v6, 0xffff0000, v2
	global_load_dwordx4 v[0:3], v[94:95], off offset:16
	global_load_dwordx4 v[24:27], v[94:95], off
	v_pk_add_f32 v[10:11], v[10:11], v[8:9]
	v_pk_add_f32 v[4:5], v[4:5], v[16:17]
	v_mov_b32_e32 v8, v10
	v_mov_b32_e32 v9, v4
	v_pk_add_f32 v[18:19], v[12:13], v[18:19]
	v_pk_fma_f32 v[8:9], v[8:9], 0.5, v[28:29] op_sel_hi:[1,0,1] neg_lo:[0,0,1] neg_hi:[0,0,1]
	v_mov_b32_e32 v4, v11
	v_pk_fma_f32 v[4:5], v[4:5], 0.5, v[30:31] op_sel_hi:[1,0,1] neg_lo:[0,0,1] neg_hi:[0,0,1]
	v_pk_add_f32 v[14:15], v[14:15], v[20:21]
	s_waitcnt vmcnt(1)
	v_mov_b32_e32 v17, v2
	s_waitcnt vmcnt(0)
	v_mov_b32_e32 v12, v24
	v_mov_b32_e32 v13, v26
	v_pk_fma_f32 v[8:9], v[12:13], v[8:9], v[28:29]
	v_mov_b32_e32 v26, v25
	v_pk_fma_f32 v[10:11], v[26:27], v[4:5], v[30:31]
	v_and_b32_sdwa v5, v8, v207 dst_sel:DWORD dst_unused:UNUSED_PAD src0_sel:WORD_1 src1_sel:DWORD
	v_add3_u32 v12, v8, v5, s31
	v_and_b32_sdwa v5, v11, v207 dst_sel:DWORD dst_unused:UNUSED_PAD src0_sel:WORD_1 src1_sel:DWORD
	v_and_b32_sdwa v13, v10, v207 dst_sel:DWORD dst_unused:UNUSED_PAD src0_sel:WORD_1 src1_sel:DWORD
	v_and_b32_sdwa v4, v9, v207 dst_sel:DWORD dst_unused:UNUSED_PAD src0_sel:WORD_1 src1_sel:DWORD
	v_add3_u32 v5, v11, v5, s31
	v_add3_u32 v13, v10, v13, s31
	v_add3_u32 v4, v9, v4, s31
	v_and_b32_e32 v5, 0xffff0000, v5
	v_and_b32_e32 v13, 0xffff0000, v13
	v_or_b32_sdwa v5, v5, v4 dst_sel:DWORD dst_unused:UNUSED_PAD src0_sel:DWORD src1_sel:WORD_1
	v_or_b32_sdwa v4, v13, v12 dst_sel:DWORD dst_unused:UNUSED_PAD src0_sel:DWORD src1_sel:WORD_1
	v_mov_b32_e32 v13, v18
	v_mov_b32_e32 v18, v15
	v_mov_b32_e32 v12, v14
	v_pk_fma_f32 v[14:15], v[18:19], 0.5, v[6:7] op_sel_hi:[1,0,1] neg_lo:[0,0,1] neg_hi:[0,0,1]
	v_mov_b32_e32 v2, v1
	v_pk_fma_f32 v[12:13], v[12:13], 0.5, v[32:33] op_sel_hi:[1,0,1] neg_lo:[0,0,1] neg_hi:[0,0,1]
	v_mov_b32_e32 v16, v0
	v_pk_fma_f32 v[2:3], v[14:15], v[2:3], v[6:7]
	v_pk_fma_f32 v[12:13], v[12:13], v[16:17], v[32:33]
	v_and_b32_sdwa v6, v3, v207 dst_sel:DWORD dst_unused:UNUSED_PAD src0_sel:WORD_1 src1_sel:DWORD
	v_and_b32_sdwa v7, v2, v207 dst_sel:DWORD dst_unused:UNUSED_PAD src0_sel:WORD_1 src1_sel:DWORD
	v_and_b32_sdwa v0, v13, v207 dst_sel:DWORD dst_unused:UNUSED_PAD src0_sel:WORD_1 src1_sel:DWORD
	v_and_b32_sdwa v1, v12, v207 dst_sel:DWORD dst_unused:UNUSED_PAD src0_sel:WORD_1 src1_sel:DWORD
	v_add3_u32 v6, v3, v6, s31
	v_add3_u32 v7, v2, v7, s31
	v_add3_u32 v1, v12, v1, s31
	v_add3_u32 v0, v13, v0, s31
	v_and_b32_e32 v6, 0xffff0000, v6
	v_and_b32_e32 v14, 0xffff0000, v7
	v_or_b32_sdwa v7, v6, v0 dst_sel:DWORD dst_unused:UNUSED_PAD src0_sel:DWORD src1_sel:WORD_1
	v_or_b32_sdwa v6, v14, v1 dst_sel:DWORD dst_unused:UNUSED_PAD src0_sel:DWORD src1_sel:WORD_1
	v_mad_i64_i32 v[0:1], s[6:7], v22, s0, v[102:103]
	s_mov_b64 s[6:7], exec
	v_readlane_b32 s18, v255, 47
	v_readlane_b32 s19, v255, 48
	s_and_b64 s[18:19], s[6:7], s[18:19]
	s_xor_b64 s[52:53], s[18:19], s[6:7]
	s_mov_b64 exec, s[18:19]
	s_cbranch_execz .LBB0_619
	s_mov_b64 s[6:7], exec
	v_readlane_b32 s18, v255, 49
	v_readlane_b32 s19, v255, 50
	s_and_b64 s[18:19], s[6:7], s[18:19]
	s_xor_b64 s[56:57], s[18:19], s[6:7]
	s_mov_b64 exec, s[18:19]
	s_cbranch_execz .LBB0_616
; #define UFOR(v, n) _Pragma("unroll") for (int v = 0; v < (n); ++v)
; __device__ __forceinline__ void phase_features(KP p, int l) {
;     ...
;       else {
;         *(uint4*)(smem + F_KL + (tok * RW + ch) * 2) = pk;
;         float kc[8], kq[8]; ld8f(kk_ + ch, kc);
;         float ss = 0.f;
;         UFOR(x, 8) { kq[x] = o[x] * kc[x]; ss += kq[x] * kq[x]; }
;         ss += dppf<0xB1>(ss); ss += dppf<0x4E>(ss); ss += dppf<0x141>(ss);
;         const float inv = 1.f / fmaxf(sqrtf(ss), 1e-12f);
;         UFOR(x, 8) kq[x] *= inv;
;         const uint4 pq = pack8(kq);
;         *(uint4*)(FA(1) + go) = pq; *(uint4*)(smem + F_KK + (tok * RW + ch) * 2) = pq;
	v_add_u32_e32 v20, 0, v182
	ds_write_b128 v20, v[4:7] offset:8448
	global_load_dwordx4 v[4:7], v[108:109], off offset:16
	global_load_dwordx4 v[14:17], v[108:109], off
	s_mov_b32 s1, 0xf800000
	v_lshl_add_u64 v[0:1], v[0:1], 1, s[76:77]
	s_waitcnt vmcnt(0)
	v_mov_b32_e32 v18, v14
	v_mov_b32_e32 v19, v16
	v_mov_b32_e32 v16, v15
	v_pk_mul_f32 v[8:9], v[8:9], v[18:19]
	v_pk_mul_f32 v[10:11], v[10:11], v[16:17]
	v_mov_b32_e32 v16, v4
	v_mov_b32_e32 v17, v6
	v_mov_b32_e32 v14, v9
	v_mov_b32_e32 v15, v11
	v_pk_mul_f32 v[12:13], v[12:13], v[16:17]
	v_mov_b32_e32 v6, v5
	v_mul_f32_e32 v16, v8, v8
	v_pk_mul_f32 v[14:15], v[14:15], v[14:15]
	v_pk_mul_f32 v[2:3], v[2:3], v[6:7]
	v_fmac_f32_e32 v16, v10, v10
	v_mov_b32_e32 v4, v12
	v_mov_b32_e32 v5, v2
	v_add_f32_e32 v14, v16, v14
	v_pk_mul_f32 v[4:5], v[4:5], v[4:5]
	v_add_f32_e32 v14, v14, v15
	v_mov_b32_e32 v6, v13
	v_mov_b32_e32 v7, v3
	v_add_f32_e32 v4, v14, v4
	v_pk_mul_f32 v[6:7], v[6:7], v[6:7]
	v_add_f32_e32 v4, v4, v5
	v_add_f32_e32 v4, v4, v6
	v_add_f32_e32 v4, v4, v7
	s_nop 1
	v_add_f32_dpp v4, v4, v4 quad_perm:[1,0,3,2] row_mask:0xf bank_mask:0xf bound_ctrl:1
	s_nop 1
	v_add_f32_dpp v4, v4, v4 quad_perm:[2,3,0,1] row_mask:0xf bank_mask:0xf bound_ctrl:1
	s_nop 1
	v_add_f32_dpp v4, v4, v4 row_half_mirror row_mask:0xf bank_mask:0xf bound_ctrl:1
	v_cmp_gt_f32_e32 vcc, s1, v4
	v_mul_f32_e32 v5, 0x4f800000, v4
	s_nop 0
	v_cndmask_b32_e32 v4, v4, v5, vcc
	v_sqrt_f32_e32 v5, v4
	s_nop 0
	v_add_u32_e32 v6, -1, v5
	v_fma_f32 v7, -v6, v5, v4
	v_cmp_ge_f32_e64 s[84:85], 0, v7
	v_add_u32_e32 v7, 1, v5
	s_nop 0
	v_cndmask_b32_e64 v6, v5, v6, s[84:85]
	v_fma_f32 v5, -v7, v5, v4
	v_cmp_lt_f32_e64 s[84:85], 0, v5
	s_nop 1
	v_cndmask_b32_e64 v5, v6, v7, s[84:85]
	v_mul_f32_e32 v6, 0x37800000, v5
	v_cndmask_b32_e32 v5, v5, v6, vcc
	v_mov_b32_e32 v6, 0x260
	v_cmp_class_f32_e32 vcc, v4, v6
	s_nop 1
	v_cndmask_b32_e32 v4, v5, v4, vcc
	v_max_f32_e32 v4, 0x2b8cbccc, v4
	v_div_scale_f32 v5, s[6:7], v4, v4, 1.0
	v_rcp_f32_e32 v6, v5
	s_nop 0
	v_fma_f32 v7, -v5, v6, 1.0
	v_fmac_f32_e32 v6, v7, v6
	v_div_scale_f32 v7, vcc, 1.0, v4, 1.0
	v_mul_f32_e32 v14, v7, v6
	v_fma_f32 v15, -v5, v14, v7
	v_fmac_f32_e32 v14, v15, v6
	v_fma_f32 v5, -v5, v14, v7
	v_div_fmas_f32 v5, v5, v6, v14
	v_div_fixup_f32 v4, v5, v4, 1.0
	v_pk_mul_f32 v[6:7], v[8:9], v[4:5] op_sel_hi:[1,0]
	v_pk_mul_f32 v[8:9], v[10:11], v[4:5] op_sel_hi:[1,0]
	v_pk_mul_f32 v[10:11], v[12:13], v[4:5] op_sel_hi:[1,0]
	v_pk_mul_f32 v[4:5], v[2:3], v[4:5] op_sel_hi:[1,0]
	v_and_b32_sdwa v2, v7, v207 dst_sel:DWORD dst_unused:UNUSED_PAD src0_sel:WORD_1 src1_sel:DWORD
	v_and_b32_sdwa v3, v6, v207 dst_sel:DWORD dst_unused:UNUSED_PAD src0_sel:WORD_1 src1_sel:DWORD
	v_add3_u32 v6, v6, v3, s31
	v_add3_u32 v2, v7, v2, s31
	v_and_b32_sdwa v3, v9, v207 dst_sel:DWORD dst_unused:UNUSED_PAD src0_sel:WORD_1 src1_sel:DWORD
	v_and_b32_sdwa v7, v8, v207 dst_sel:DWORD dst_unused:UNUSED_PAD src0_sel:WORD_1 src1_sel:DWORD
	v_add3_u32 v3, v9, v3, s31
	v_add3_u32 v7, v8, v7, s31
	v_and_b32_e32 v3, 0xffff0000, v3
	v_and_b32_e32 v7, 0xffff0000, v7
	v_and_b32_sdwa v8, v5, v207 dst_sel:DWORD dst_unused:UNUSED_PAD src0_sel:WORD_1 src1_sel:DWORD
	v_and_b32_sdwa v9, v4, v207 dst_sel:DWORD dst_unused:UNUSED_PAD src0_sel:WORD_1 src1_sel:DWORD
	v_or_b32_sdwa v3, v3, v2 dst_sel:DWORD dst_unused:UNUSED_PAD src0_sel:DWORD src1_sel:WORD_1
	v_or_b32_sdwa v2, v7, v6 dst_sel:DWORD dst_unused:UNUSED_PAD src0_sel:DWORD src1_sel:WORD_1
	v_and_b32_sdwa v6, v11, v207 dst_sel:DWORD dst_unused:UNUSED_PAD src0_sel:WORD_1 src1_sel:DWORD
	v_and_b32_sdwa v7, v10, v207 dst_sel:DWORD dst_unused:UNUSED_PAD src0_sel:WORD_1 src1_sel:DWORD
	v_add3_u32 v5, v5, v8, s31
	v_add3_u32 v4, v4, v9, s31
	v_add3_u32 v7, v10, v7, s31
	v_add3_u32 v6, v11, v6, s31
	v_and_b32_e32 v5, 0xffff0000, v5
	v_and_b32_e32 v4, 0xffff0000, v4
	v_or_b32_sdwa v5, v5, v6 dst_sel:DWORD dst_unused:UNUSED_PAD src0_sel:DWORD src1_sel:WORD_1
	v_or_b32_sdwa v4, v4, v7 dst_sel:DWORD dst_unused:UNUSED_PAD src0_sel:DWORD src1_sel:WORD_1
	global_store_dwordx4 v[0:1], v[2:5], off
	ds_write_b128 v20, v[2:5] offset:33024

; #define UFOR(v, n) _Pragma("unroll") for (int v = 0; v < (n); ++v)
; __device__ __forceinline__ void phase_features(KP p, int l) {
;     ...
;       const int q = tid_ + 512 * i, tok = q / 288, grp = q % 288, sec = grp / 96, r = R0 + tok, col = grp * 8, ch = col - sec * RW;
;       const bool hm = r - 1 >= s0, hp = r + 1 < s0 + len;
;       const u16* z = zrw + (size_t)r * RWC + col;
;       float c[8], a[8], b[8], o[8], m[8];
;       unpack8(*(const uint4*)z, c);
;       if (hm) unpack8(*(const uint4*)(z - RWC), a); else UFOR(x, 8) a[x] = 0.f;
.LBB0_621:
	s_or_b64 exec, exec, s[52:53]
	v_add_u32_e32 v22, s15, v180
	s_movk_i32 s1, 0x1400
	v_mad_i64_i32 v[6:7], s[6:7], v22, s1, v[116:117]
	global_load_dwordx4 v[0:3], v[6:7], off
	v_cmp_lt_i32_e32 vcc, s38, v22
	v_mov_b32_e32 v14, 0
	v_mov_b32_e32 v15, 0
	v_mov_b32_e32 v16, 0
	v_mov_b32_e32 v17, 0
	v_mov_b32_e32 v212, 0
	v_mov_b32_e32 v213, 0
	v_mov_b32_e32 v214, 0
	v_mov_b32_e32 v215, 0
	s_and_saveexec_b64 s[52:53], vcc
	s_cbranch_execz .LBB0_623
	v_add_co_u32_e32 v4, vcc, 0xfffff000, v6
	s_nop 1
	v_addc_co_u32_e32 v5, vcc, -1, v7, vcc
	global_load_dwordx4 v[14:17], v[4:5], off offset:-1024

; #define UFOR(v, n) _Pragma("unroll") for (int v = 0; v < (n); ++v)
; __device__ __forceinline__ void phase_features(KP p, int l) {
;     ...
;       const bool hm = r - 1 >= s0, hp = r + 1 < s0 + len;
;       const u16* z = zrw + (size_t)r * RWC + col;
;       float c[8], a[8], b[8], o[8], m[8];
;       unpack8(*(const uint4*)z, c);
;       if (hm) unpack8(*(const uint4*)(z - RWC), a); else UFOR(x, 8) a[x] = 0.f;
;       if (hp) unpack8(*(const uint4*)(z + RWC), b); else UFOR(x, 8) b[x] = 0.f;
;       ld8f(mu + col, m);
;       UFOR(x, 8) o[x] = c[x] + (0.5f * (a[x] + b[x]) - c[x]) * m[x];
;       const uint4 pk = pack8(o);
;       const size_t go = (size_t)r * RW + ch;
;       if (sec == 0) { *(uint4*)(FA(0) + go) = pk; *(uint4*)(smem + F_RL + (tok * RW + ch) * 2) = pk; }
;       else if (sec == 2) { *(uint4*)(FA(2) + go) = pk; }
;       else {
;         *(uint4*)(smem + F_KL + (tok * RW + ch) * 2) = pk;
.LBB0_625:
	s_or_b64 exec, exec, s[52:53]
	s_waitcnt vmcnt(0)
	v_lshlrev_b32_e32 v10, 16, v14
	v_and_b32_e32 v11, 0xffff0000, v14
	v_lshlrev_b32_e32 v4, 16, v15
	v_and_b32_e32 v5, 0xffff0000, v15
	v_lshlrev_b32_e32 v14, 16, v16
	v_and_b32_e32 v15, 0xffff0000, v16
	v_lshlrev_b32_e32 v12, 16, v17
	v_and_b32_e32 v13, 0xffff0000, v17
	v_lshlrev_b32_e32 v8, 16, v212
	v_and_b32_e32 v9, 0xffff0000, v212
	v_lshlrev_b32_e32 v16, 16, v213
	v_and_b32_e32 v17, 0xffff0000, v213
	v_lshlrev_b32_e32 v20, 16, v214
	v_and_b32_e32 v21, 0xffff0000, v214
	v_lshlrev_b32_e32 v18, 16, v215
	v_and_b32_e32 v19, 0xffff0000, v215
	v_lshlrev_b32_e32 v29, 16, v1
	v_lshlrev_b32_e32 v28, 16, v0
	v_and_b32_e32 v31, 0xffff0000, v1
	v_and_b32_e32 v30, 0xffff0000, v0
	v_lshlrev_b32_e32 v33, 16, v3
	v_lshlrev_b32_e32 v32, 16, v2
	v_and_b32_e32 v7, 0xffff0000, v3
	v_and_b32_e32 v6, 0xffff0000, v2
	global_load_dwordx4 v[0:3], v[96:97], off offset:16
	global_load_dwordx4 v[24:27], v[96:97], off
	v_pk_add_f32 v[10:11], v[10:11], v[8:9]
	v_pk_add_f32 v[4:5], v[4:5], v[16:17]
	v_mov_b32_e32 v8, v10
	v_mov_b32_e32 v9, v4
	v_pk_add_f32 v[18:19], v[12:13], v[18:19]
	v_pk_fma_f32 v[8:9], v[8:9], 0.5, v[28:29] op_sel_hi:[1,0,1] neg_lo:[0,0,1] neg_hi:[0,0,1]
	v_mov_b32_e32 v4, v11
	v_pk_fma_f32 v[4:5], v[4:5], 0.5, v[30:31] op_sel_hi:[1,0,1] neg_lo:[0,0,1] neg_hi:[0,0,1]
	v_pk_add_f32 v[14:15], v[14:15], v[20:21]
	s_waitcnt vmcnt(1)
	v_mov_b32_e32 v17, v2
	s_waitcnt vmcnt(0)
	v_mov_b32_e32 v12, v24
	v_mov_b32_e32 v13, v26
	v_pk_fma_f32 v[8:9], v[12:13], v[8:9], v[28:29]
	v_mov_b32_e32 v26, v25
	v_pk_fma_f32 v[10:11], v[26:27], v[4:5], v[30:31]
	v_and_b32_sdwa v5, v8, v207 dst_sel:DWORD dst_unused:UNUSED_PAD src0_sel:WORD_1 src1_sel:DWORD
	v_add3_u32 v12, v8, v5, s31
	v_and_b32_sdwa v5, v11, v207 dst_sel:DWORD dst_unused:UNUSED_PAD src0_sel:WORD_1 src1_sel:DWORD
	v_and_b32_sdwa v13, v10, v207 dst_sel:DWORD dst_unused:UNUSED_PAD src0_sel:WORD_1 src1_sel:DWORD
	v_and_b32_sdwa v4, v9, v207 dst_sel:DWORD dst_unused:UNUSED_PAD src0_sel:WORD_1 src1_sel:DWORD
	v_add3_u32 v5, v11, v5, s31
	v_add3_u32 v13, v10, v13, s31
	v_add3_u32 v4, v9, v4, s31
	v_and_b32_e32 v5, 0xffff0000, v5
	v_and_b32_e32 v13, 0xffff0000, v13
	v_or_b32_sdwa v5, v5, v4 dst_sel:DWORD dst_unused:UNUSED_PAD src0_sel:DWORD src1_sel:WORD_1
	v_or_b32_sdwa v4, v13, v12 dst_sel:DWORD dst_unused:UNUSED_PAD src0_sel:DWORD src1_sel:WORD_1
	v_mov_b32_e32 v13, v18
	v_mov_b32_e32 v18, v15
	v_mov_b32_e32 v12, v14
	v_pk_fma_f32 v[14:15], v[18:19], 0.5, v[6:7] op_sel_hi:[1,0,1] neg_lo:[0,0,1] neg_hi:[0,0,1]
	v_mov_b32_e32 v2, v1
	v_pk_fma_f32 v[12:13], v[12:13], 0.5, v[32:33] op_sel_hi:[1,0,1] neg_lo:[0,0,1] neg_hi:[0,0,1]
	v_mov_b32_e32 v16, v0
	v_pk_fma_f32 v[2:3], v[14:15], v[2:3], v[6:7]
	v_pk_fma_f32 v[12:13], v[12:13], v[16:17], v[32:33]
	v_and_b32_sdwa v6, v3, v207 dst_sel:DWORD dst_unused:UNUSED_PAD src0_sel:WORD_1 src1_sel:DWORD
	v_and_b32_sdwa v7, v2, v207 dst_sel:DWORD dst_unused:UNUSED_PAD src0_sel:WORD_1 src1_sel:DWORD
	v_and_b32_sdwa v0, v13, v207 dst_sel:DWORD dst_unused:UNUSED_PAD src0_sel:WORD_1 src1_sel:DWORD
	v_and_b32_sdwa v1, v12, v207 dst_sel:DWORD dst_unused:UNUSED_PAD src0_sel:WORD_1 src1_sel:DWORD
	v_add3_u32 v6, v3, v6, s31
	v_add3_u32 v7, v2, v7, s31
	v_add3_u32 v1, v12, v1, s31
	v_add3_u32 v0, v13, v0, s31
	v_and_b32_e32 v6, 0xffff0000, v6
	v_and_b32_e32 v14, 0xffff0000, v7
	v_or_b32_sdwa v7, v6, v0 dst_sel:DWORD dst_unused:UNUSED_PAD src0_sel:DWORD src1_sel:WORD_1
	v_or_b32_sdwa v6, v14, v1 dst_sel:DWORD dst_unused:UNUSED_PAD src0_sel:DWORD src1_sel:WORD_1
	v_mad_i64_i32 v[0:1], s[6:7], v22, s0, v[110:111]
	s_mov_b64 s[6:7], exec
	v_readlane_b32 s18, v255, 51
	v_readlane_b32 s19, v255, 52
	s_and_b64 s[18:19], s[6:7], s[18:19]
	s_xor_b64 s[52:53], s[18:19], s[6:7]
	s_mov_b64 exec, s[18:19]
	s_cbranch_execz .LBB0_631
	s_mov_b64 s[6:7], exec
	v_readlane_b32 s18, v255, 53
	v_readlane_b32 s19, v255, 54
	s_and_b64 s[18:19], s[6:7], s[18:19]
	s_xor_b64 s[56:57], s[18:19], s[6:7]
	s_mov_b64 exec, s[18:19]
	s_cbranch_execz .LBB0_628
; #define UFOR(v, n) _Pragma("unroll") for (int v = 0; v < (n); ++v)
; __device__ __forceinline__ void phase_features(KP p, int l) {
;     ...
;       else {
;         *(uint4*)(smem + F_KL + (tok * RW + ch) * 2) = pk;
;         float kc[8], kq[8]; ld8f(kk_ + ch, kc);
;         float ss = 0.f;
;         UFOR(x, 8) { kq[x] = o[x] * kc[x]; ss += kq[x] * kq[x]; }
;         ss += dppf<0xB1>(ss); ss += dppf<0x4E>(ss); ss += dppf<0x141>(ss);
;         const float inv = 1.f / fmaxf(sqrtf(ss), 1e-12f);
;         UFOR(x, 8) kq[x] *= inv;
;         const uint4 pq = pack8(kq);
;         *(uint4*)(FA(1) + go) = pq; *(uint4*)(smem + F_KK + (tok * RW + ch) * 2) = pq;
	v_add_u32_e32 v20, 0, v183
	ds_write_b128 v20, v[4:7] offset:8448
	global_load_dwordx4 v[4:7], v[112:113], off offset:16
	global_load_dwordx4 v[14:17], v[112:113], off
	s_mov_b32 s1, 0xf800000
	v_lshl_add_u64 v[0:1], v[0:1], 1, s[76:77]
	s_waitcnt vmcnt(0)
	v_mov_b32_e32 v18, v14
	v_mov_b32_e32 v19, v16
	v_mov_b32_e32 v16, v15
	v_pk_mul_f32 v[8:9], v[8:9], v[18:19]
	v_pk_mul_f32 v[10:11], v[10:11], v[16:17]
	v_mov_b32_e32 v16, v4
	v_mov_b32_e32 v17, v6
	v_mov_b32_e32 v14, v9
	v_mov_b32_e32 v15, v11
	v_pk_mul_f32 v[12:13], v[12:13], v[16:17]
	v_mov_b32_e32 v6, v5
	v_mul_f32_e32 v16, v8, v8
	v_pk_mul_f32 v[14:15], v[14:15], v[14:15]
	v_pk_mul_f32 v[2:3], v[2:3], v[6:7]
	v_fmac_f32_e32 v16, v10, v10
	v_mov_b32_e32 v4, v12
	v_mov_b32_e32 v5, v2
	v_add_f32_e32 v14, v16, v14
	v_pk_mul_f32 v[4:5], v[4:5], v[4:5]
	v_add_f32_e32 v14, v14, v15
	v_mov_b32_e32 v6, v13
	v_mov_b32_e32 v7, v3
	v_add_f32_e32 v4, v14, v4
	v_pk_mul_f32 v[6:7], v[6:7], v[6:7]
	v_add_f32_e32 v4, v4, v5
	v_add_f32_e32 v4, v4, v6
	v_add_f32_e32 v4, v4, v7
	s_nop 1
	v_add_f32_dpp v4, v4, v4 quad_perm:[1,0,3,2] row_mask:0xf bank_mask:0xf bound_ctrl:1
	s_nop 1
	v_add_f32_dpp v4, v4, v4 quad_perm:[2,3,0,1] row_mask:0xf bank_mask:0xf bound_ctrl:1
	s_nop 1
	v_add_f32_dpp v4, v4, v4 row_half_mirror row_mask:0xf bank_mask:0xf bound_ctrl:1
	v_cmp_gt_f32_e32 vcc, s1, v4
	v_mul_f32_e32 v5, 0x4f800000, v4
	s_nop 0
	v_cndmask_b32_e32 v4, v4, v5, vcc
	v_sqrt_f32_e32 v5, v4
	s_nop 0
	v_add_u32_e32 v6, -1, v5
	v_fma_f32 v7, -v6, v5, v4
	v_cmp_ge_f32_e64 s[84:85], 0, v7
	v_add_u32_e32 v7, 1, v5
	s_nop 0
	v_cndmask_b32_e64 v6, v5, v6, s[84:85]
	v_fma_f32 v5, -v7, v5, v4
	v_cmp_lt_f32_e64 s[84:85], 0, v5
	s_nop 1
	v_cndmask_b32_e64 v5, v6, v7, s[84:85]
	v_mul_f32_e32 v6, 0x37800000, v5
	v_cndmask_b32_e32 v5, v5, v6, vcc
	v_mov_b32_e32 v6, 0x260
	v_cmp_class_f32_e32 vcc, v4, v6
	s_nop 1
	v_cndmask_b32_e32 v4, v5, v4, vcc
	v_max_f32_e32 v4, 0x2b8cbccc, v4
	v_div_scale_f32 v5, s[6:7], v4, v4, 1.0
	v_rcp_f32_e32 v6, v5
	s_nop 0
	v_fma_f32 v7, -v5, v6, 1.0
	v_fmac_f32_e32 v6, v7, v6
	v_div_scale_f32 v7, vcc, 1.0, v4, 1.0
	v_mul_f32_e32 v14, v7, v6
	v_fma_f32 v15, -v5, v14, v7
	v_fmac_f32_e32 v14, v15, v6
	v_fma_f32 v5, -v5, v14, v7
	v_div_fmas_f32 v5, v5, v6, v14
	v_div_fixup_f32 v4, v5, v4, 1.0
	v_pk_mul_f32 v[6:7], v[8:9], v[4:5] op_sel_hi:[1,0]
	v_pk_mul_f32 v[8:9], v[10:11], v[4:5] op_sel_hi:[1,0]
	v_pk_mul_f32 v[10:11], v[12:13], v[4:5] op_sel_hi:[1,0]
	v_pk_mul_f32 v[4:5], v[2:3], v[4:5] op_sel_hi:[1,0]
	v_and_b32_sdwa v2, v7, v207 dst_sel:DWORD dst_unused:UNUSED_PAD src0_sel:WORD_1 src1_sel:DWORD
	v_and_b32_sdwa v3, v6, v207 dst_sel:DWORD dst_unused:UNUSED_PAD src0_sel:WORD_1 src1_sel:DWORD
	v_add3_u32 v6, v6, v3, s31
	v_add3_u32 v2, v7, v2, s31
	v_and_b32_sdwa v3, v9, v207 dst_sel:DWORD dst_unused:UNUSED_PAD src0_sel:WORD_1 src1_sel:DWORD
	v_and_b32_sdwa v7, v8, v207 dst_sel:DWORD dst_unused:UNUSED_PAD src0_sel:WORD_1 src1_sel:DWORD
	v_add3_u32 v3, v9, v3, s31
	v_add3_u32 v7, v8, v7, s31
	v_and_b32_e32 v3, 0xffff0000, v3
	v_and_b32_e32 v7, 0xffff0000, v7
	v_and_b32_sdwa v8, v5, v207 dst_sel:DWORD dst_unused:UNUSED_PAD src0_sel:WORD_1 src1_sel:DWORD
	v_and_b32_sdwa v9, v4, v207 dst_sel:DWORD dst_unused:UNUSED_PAD src0_sel:WORD_1 src1_sel:DWORD
	v_or_b32_sdwa v3, v3, v2 dst_sel:DWORD dst_unused:UNUSED_PAD src0_sel:DWORD src1_sel:WORD_1
	v_or_b32_sdwa v2, v7, v6 dst_sel:DWORD dst_unused:UNUSED_PAD src0_sel:DWORD src1_sel:WORD_1
	v_and_b32_sdwa v6, v11, v207 dst_sel:DWORD dst_unused:UNUSED_PAD src0_sel:WORD_1 src1_sel:DWORD
	v_and_b32_sdwa v7, v10, v207 dst_sel:DWORD dst_unused:UNUSED_PAD src0_sel:WORD_1 src1_sel:DWORD
	v_add3_u32 v5, v5, v8, s31
	v_add3_u32 v4, v4, v9, s31
	v_add3_u32 v7, v10, v7, s31
	v_add3_u32 v6, v11, v6, s31
	v_and_b32_e32 v5, 0xffff0000, v5
	v_and_b32_e32 v4, 0xffff0000, v4
	v_or_b32_sdwa v5, v5, v6 dst_sel:DWORD dst_unused:UNUSED_PAD src0_sel:DWORD src1_sel:WORD_1
	v_or_b32_sdwa v4, v4, v7 dst_sel:DWORD dst_unused:UNUSED_PAD src0_sel:DWORD src1_sel:WORD_1
	global_store_dwordx4 v[0:1], v[2:5], off
	ds_write_b128 v20, v[2:5] offset:33024

; #define UFOR(v, n) _Pragma("unroll") for (int v = 0; v < (n); ++v)
; __device__ __forceinline__ float sigmoidf_(float x) { return 1.f / (1.f + __expf(-x)); }
; __device__ __forceinline__ void phase_features(KP p, int l) {
;     ...
;     {
;       const int tok = tid_ >> 5, cg = tid_ & 31, r = R0 + tok;
;       const bool hm = r - 1 >= s0, hp = r + 1 < s0 + len;
;       const u16* z = zrw + (size_t)r * RWC + 2304 + cg * 8;
;       float c[8], a[8], b[8], o[8], m[8];
;       unpack8(*(const uint4*)z, c);
;       if (hm) unpack8(*(const uint4*)(z - RWC), a); else UFOR(x, 8) a[x] = 0.f;
;       if (hp) unpack8(*(const uint4*)(z + RWC), b); else UFOR(x, 8) b[x] = 0.f;
;       ld8f(mu + 2304 + cg * 8, m);
;       UFOR(x, 8) {
;         const float v = c[x] + (0.5f * (a[x] + b[x]) - c[x]) * m[x];
;         o[x] = (cg < 8) ? (1.f - 2.f / (1.f + __expf(2.f * v))) : ((cg < 16) ? v : sigmoidf_(v));
;       }
;       *(uint4*)(smem + F_AIN + tok * 528 + cg * 16) = pack8(o);
.LBB0_633:
	s_or_b64 exec, exec, s[52:53]
	v_add_u32_e32 v6, s15, v158
	v_mov_b64_e32 v[0:1], s[78:79]
	s_movk_i32 s1, 0x1400
	v_mad_i64_i32 v[0:1], s[6:7], v6, s1, v[0:1]
	v_lshl_add_u64 v[4:5], v[0:1], 0, v[132:133]
	v_add_co_u32_e32 v0, vcc, 0x1000, v4
	s_mov_b64 s[6:7], 0x1200
	s_nop 0
	v_addc_co_u32_e32 v1, vcc, 0, v5, vcc
	global_load_dwordx4 v[0:3], v[0:1], off offset:512
	v_cmp_lt_i32_e32 vcc, s38, v6
	v_lshl_add_u64 v[4:5], v[4:5], 0, s[6:7]
	v_mov_b32_e32 v8, 0
	v_mov_b32_e32 v9, 0
	v_mov_b32_e32 v10, 0
	v_mov_b32_e32 v11, 0
	v_mov_b32_e32 v212, 0
	v_mov_b32_e32 v213, 0
	v_mov_b32_e32 v214, 0
	v_mov_b32_e32 v215, 0
	s_and_saveexec_b64 s[52:53], vcc
	s_cbranch_execz .LBB0_635
	v_add_co_u32_e32 v8, vcc, 0xfffff000, v4
	s_nop 1
	v_addc_co_u32_e32 v9, vcc, -1, v5, vcc
	global_load_dwordx4 v[8:11], v[8:9], off offset:-1024
.LBB0_635:
	s_or_b64 exec, exec, s[52:53]
	v_add_u32_e32 v6, 1, v6
	v_cmp_gt_i32_e32 vcc, s39, v6
	s_and_saveexec_b64 s[52:53], vcc
	s_cbranch_execz .LBB0_637
	v_add_co_u32_e32 v4, vcc, 0x1000, v4
	s_nop 1
	v_addc_co_u32_e32 v5, vcc, 0, v5, vcc
	global_load_dwordx4 v[212:215], v[4:5], off offset:1024
.LBB0_637:
	s_or_b64 exec, exec, s[52:53]
	s_waitcnt vmcnt(0)
	v_lshlrev_b32_e32 v26, 16, v8
	v_and_b32_e32 v27, 0xffff0000, v8
	v_lshlrev_b32_e32 v20, 16, v9
	v_and_b32_e32 v21, 0xffff0000, v9
	v_lshlrev_b32_e32 v16, 16, v10
	v_and_b32_e32 v17, 0xffff0000, v10
	v_lshlrev_b32_e32 v12, 16, v11
	v_and_b32_e32 v13, 0xffff0000, v11
	v_lshlrev_b32_e32 v24, 16, v212
	v_and_b32_e32 v25, 0xffff0000, v212
	v_lshlrev_b32_e32 v22, 16, v213
	v_and_b32_e32 v23, 0xffff0000, v213
	v_lshlrev_b32_e32 v18, 16, v214
	v_and_b32_e32 v19, 0xffff0000, v214
	v_lshlrev_b32_e32 v14, 16, v215
	v_and_b32_e32 v15, 0xffff0000, v215
	global_load_dwordx4 v[8:11], v[36:37], off
	global_load_dwordx4 v[4:7], v[36:37], off offset:16
	s_waitcnt vmcnt(2)
	v_lshlrev_b32_e32 v28, 16, v0
	v_pk_add_f32 v[24:25], v[26:27], v[24:25]
	s_nop 0
	v_fma_f32 v24, v24, 0.5, -v28
	s_waitcnt vmcnt(1)
	v_fmac_f32_e32 v28, v24, v8
	s_and_saveexec_b64 s[6:7], s[40:41]
	s_xor_b64 s[52:53], exec, s[6:7]
	s_cbranch_execz .LBB0_641
	s_and_saveexec_b64 s[56:57], s[42:43]
	s_cbranch_execz .LBB0_640
	v_mul_f32_e32 v8, 0xbfb8aa3b, v28
	v_exp_f32_e32 v8, v8
	s_nop 0
	v_add_f32_e32 v8, 1.0, v8
	v_div_scale_f32 v24, s[6:7], v8, v8, 1.0
	v_rcp_f32_e32 v26, v24
	v_div_scale_f32 v27, vcc, 1.0, v8, 1.0
	v_fma_f32 v28, -v24, v26, 1.0
	v_fmac_f32_e32 v26, v28, v26
	v_mul_f32_e32 v28, v27, v26
	v_fma_f32 v29, -v24, v28, v27
	v_fmac_f32_e32 v28, v29, v26
	v_fma_f32 v24, -v24, v28, v27
	v_div_fmas_f32 v24, v24, v26, v28
	v_div_fixup_f32 v28, v24, v8, 1.0
